# static priority: younger half raised inside the GEMM main loops, older half raised through the epilogue and its next-unit entry; per-segment flips deleted
# speedup vs baseline: 1.0010x; 1.0010x over previous
.LBB0_445:
	s_add_u32 s56, s62, 0xb0080
	s_addc_u32 s57, s63, 0
	s_add_u32 s62, s60, 0x100
	v_mov_b32_e32 v2, 0
	s_addc_u32 s63, s61, 0
	s_mov_b32 s84, -2
	s_waitcnt lgkmcnt(0)
	s_add_i32 s22, 0, 0x10000
	s_add_i32 s23, 0, 0x14000
	v_add_u32_e32 v134, s22, v191
	v_add_u32_e32 v182, s23, v191
	ds_read_b128 v[114:117], v134
	ds_read_b128 v[126:129], v134 offset:1024
	ds_read_b128 v[130:133], v134 offset:2048
	ds_read_b128 v[134:137], v134 offset:3072
	ds_read_b128 v[146:149], v182
	ds_read_b128 v[150:153], v182 offset:1024
	ds_read_b128 v[158:161], v182 offset:2048
	ds_read_b128 v[182:185], v182 offset:3072
	ds_read_b128 v[186:189], v193
	ds_read_b128 v[194:197], v193 offset:1024
	ds_read_b128 v[198:201], v193 offset:2048
	ds_read_b128 v[214:217], v193 offset:3072
	ds_read_b128 v[218:221], v193 offset:4096
	ds_read_b128 v[222:225], v193 offset:5120
	ds_read_b128 v[226:229], v193 offset:6144
	ds_read_b128 v[230:233], v193 offset:7168
	s_mov_b64 s[12:13], 0xb0000
	s_mov_b64 s[86:87], 0x108000
	s_mov_b64 s[96:97], 0x58080
	s_mov_b64 vcc, 0xb0080
	s_mov_b64 s[0:1], 0x108080
	s_setprio 0
	s_cmp_eq_u64 s[40:41], 0
	s_cbranch_scc0 .Lpr_446
	s_setprio 1

.LBB0_446:
	s_add_i32 s22, 0, 0x10000
	s_add_i32 s23, 0, 0x14000
	v_add_u32_e32 v134, s22, v191
	v_add_u32_e32 v162, s23, v191
	ds_read_b128 v[114:117], v134
	ds_read_b128 v[126:129], v134 offset:1024
	ds_read_b128 v[130:133], v134 offset:2048
	ds_read_b128 v[134:137], v134 offset:3072
	ds_read_b128 v[146:149], v162
	ds_read_b128 v[150:153], v162 offset:1024
	ds_read_b128 v[158:161], v162 offset:2048
	ds_read_b128 v[182:185], v162 offset:3072
	ds_read_b128 v[186:189], v193
	ds_read_b128 v[194:197], v193 offset:1024
	ds_read_b128 v[198:201], v193 offset:2048
	ds_read_b128 v[214:217], v193 offset:3072
	ds_read_b128 v[218:221], v193 offset:4096
	ds_read_b128 v[222:225], v193 offset:5120
	ds_read_b128 v[226:229], v193 offset:6144
	ds_read_b128 v[230:233], v193 offset:7168
	s_add_u32 s20, s56, 0xfff50080
	s_addc_u32 s21, s57, -1
	s_cmp_eq_u32 s84, 40
	s_cselect_b32 s61, s49, s21
	s_cselect_b32 s60, s48, s20
	s_cselect_b32 s21, s51, s63
	s_cselect_b32 s20, s50, s62
	s_add_i32 m0, s47, 0xc000
	v_lshl_add_u64 v[162:163], s[56:57], 0, v[156:157]
	global_load_lds_dwordx4 v[162:163], off
	v_lshl_add_u64 v[162:163], v[162:163], 0, s[2:3]
	s_add_i32 m0, s47, 0xe000
	s_nop 0
	global_load_lds_dwordx4 v[162:163], off
	s_waitcnt vmcnt(8)
	s_waitcnt lgkmcnt(0)
	s_barrier
	s_waitcnt lgkmcnt(0)
	v_mfma_f32_16x16x32_bf16 v[142:145], v[114:117], v[186:189], v[142:145]
	v_mfma_f32_16x16x32_bf16 v[142:145], v[126:129], v[194:197], v[142:145]
	v_mfma_f32_16x16x32_bf16 v[138:141], v[130:133], v[186:189], v[138:141]
	v_mfma_f32_16x16x32_bf16 v[138:141], v[134:137], v[194:197], v[138:141]
	v_mfma_f32_16x16x32_bf16 v[110:113], v[114:117], v[198:201], v[110:113]
	v_mfma_f32_16x16x32_bf16 v[110:113], v[126:129], v[214:217], v[110:113]
	v_mfma_f32_16x16x32_bf16 v[106:109], v[130:133], v[198:201], v[106:109]
	v_mfma_f32_16x16x32_bf16 v[106:109], v[134:137], v[214:217], v[106:109]
	v_mfma_f32_16x16x32_bf16 v[94:97], v[114:117], v[218:221], v[94:97]
	v_mfma_f32_16x16x32_bf16 v[94:97], v[126:129], v[222:225], v[94:97]
	v_mfma_f32_16x16x32_bf16 v[90:93], v[130:133], v[218:221], v[90:93]
	v_mfma_f32_16x16x32_bf16 v[90:93], v[134:137], v[222:225], v[90:93]
	v_mfma_f32_16x16x32_bf16 v[78:81], v[114:117], v[226:229], v[78:81]
	v_mfma_f32_16x16x32_bf16 v[78:81], v[126:129], v[230:233], v[78:81]
	v_mfma_f32_16x16x32_bf16 v[74:77], v[130:133], v[226:229], v[74:77]
	v_mfma_f32_16x16x32_bf16 v[74:77], v[134:137], v[230:233], v[74:77]
	v_mfma_f32_16x16x32_bf16 v[122:125], v[146:149], v[186:189], v[122:125]
	v_mfma_f32_16x16x32_bf16 v[122:125], v[150:153], v[194:197], v[122:125]
	v_mfma_f32_16x16x32_bf16 v[118:121], v[158:161], v[186:189], v[118:121]
	v_mfma_f32_16x16x32_bf16 v[118:121], v[182:185], v[194:197], v[118:121]
	v_mfma_f32_16x16x32_bf16 v[102:105], v[146:149], v[198:201], v[102:105]
	v_mfma_f32_16x16x32_bf16 v[102:105], v[150:153], v[214:217], v[102:105]
	v_mfma_f32_16x16x32_bf16 v[98:101], v[158:161], v[198:201], v[98:101]
	v_mfma_f32_16x16x32_bf16 v[98:101], v[182:185], v[214:217], v[98:101]
	v_mfma_f32_16x16x32_bf16 v[86:89], v[146:149], v[218:221], v[86:89]
	v_mfma_f32_16x16x32_bf16 v[86:89], v[150:153], v[222:225], v[86:89]
	v_mfma_f32_16x16x32_bf16 v[82:85], v[158:161], v[218:221], v[82:85]
	v_mfma_f32_16x16x32_bf16 v[82:85], v[182:185], v[222:225], v[82:85]
	v_mfma_f32_16x16x32_bf16 v[70:73], v[146:149], v[226:229], v[70:73]
	v_mfma_f32_16x16x32_bf16 v[70:73], v[150:153], v[230:233], v[70:73]
	v_mfma_f32_16x16x32_bf16 v[66:69], v[158:161], v[226:229], v[66:69]
	v_mfma_f32_16x16x32_bf16 v[66:69], v[182:185], v[230:233], v[66:69]
	s_barrier
	ds_read_b128 v[186:189], v193 offset:16384
	ds_read_b128 v[194:197], v193 offset:17408
	ds_read_b128 v[198:201], v193 offset:18432
	ds_read_b128 v[214:217], v193 offset:19456
	ds_read_b128 v[218:221], v193 offset:20480
	ds_read_b128 v[222:225], v193 offset:21504
	ds_read_b128 v[226:229], v193 offset:22528
	ds_read_b128 v[230:233], v193 offset:23552
	v_lshl_add_u64 v[162:163], s[20:21], 0, v[0:1]
	s_add_i32 s20, s22, s46
	s_mov_b32 m0, s20
	s_nop 0
	s_nop 0
	global_load_lds_dwordx4 v[162:163], off
	v_lshl_add_u64 v[202:203], v[162:163], 0, s[2:3]
	s_add_i32 m0, s20, 0x2000
	s_add_i32 s20, s23, s46
	global_load_lds_dwordx4 v[202:203], off
	v_lshl_add_u64 v[202:203], v[162:163], 0, s[12:13]
	s_mov_b32 m0, s20
	s_nop 0
	global_load_lds_dwordx4 v[202:203], off
	v_lshl_add_u64 v[202:203], v[162:163], 0, s[86:87]
	s_add_i32 m0, s20, 0x2000
	s_nop 0
	global_load_lds_dwordx4 v[202:203], off
	v_lshl_add_u64 v[202:203], s[60:61], 0, v[154:155]
	s_mov_b32 m0, s47
	v_lshl_add_u64 v[234:235], v[202:203], 0, s[2:3]
	global_load_lds_dwordx4 v[202:203], off
	s_mov_b32 m0, s68
	s_nop 0
	global_load_lds_dwordx4 v[234:235], off
	s_waitcnt vmcnt(8)
	s_waitcnt lgkmcnt(0)
	s_barrier
	s_waitcnt lgkmcnt(0)
	v_mfma_f32_16x16x32_bf16 v[62:65], v[114:117], v[186:189], v[62:65]
	v_mfma_f32_16x16x32_bf16 v[62:65], v[126:129], v[194:197], v[62:65]
	v_mfma_f32_16x16x32_bf16 v[58:61], v[130:133], v[186:189], v[58:61]
	v_mfma_f32_16x16x32_bf16 v[58:61], v[134:137], v[194:197], v[58:61]
	v_mfma_f32_16x16x32_bf16 v[46:49], v[114:117], v[198:201], v[46:49]
	v_mfma_f32_16x16x32_bf16 v[46:49], v[126:129], v[214:217], v[46:49]
	v_mfma_f32_16x16x32_bf16 v[42:45], v[130:133], v[198:201], v[42:45]
	v_mfma_f32_16x16x32_bf16 v[42:45], v[134:137], v[214:217], v[42:45]
	v_mfma_f32_16x16x32_bf16 v[30:33], v[114:117], v[218:221], v[30:33]
	v_mfma_f32_16x16x32_bf16 v[30:33], v[126:129], v[222:225], v[30:33]
	v_mfma_f32_16x16x32_bf16 v[26:29], v[130:133], v[218:221], v[26:29]
	v_mfma_f32_16x16x32_bf16 v[26:29], v[134:137], v[222:225], v[26:29]
	v_mfma_f32_16x16x32_bf16 v[14:17], v[114:117], v[226:229], v[14:17]
	v_mfma_f32_16x16x32_bf16 v[14:17], v[126:129], v[230:233], v[14:17]
	v_mfma_f32_16x16x32_bf16 v[10:13], v[130:133], v[226:229], v[10:13]
	v_mfma_f32_16x16x32_bf16 v[10:13], v[134:137], v[230:233], v[10:13]
	v_mfma_f32_16x16x32_bf16 v[54:57], v[146:149], v[186:189], v[54:57]
	v_mfma_f32_16x16x32_bf16 v[54:57], v[150:153], v[194:197], v[54:57]
	v_mfma_f32_16x16x32_bf16 v[50:53], v[158:161], v[186:189], v[50:53]
	v_mfma_f32_16x16x32_bf16 v[50:53], v[182:185], v[194:197], v[50:53]
	v_mfma_f32_16x16x32_bf16 v[38:41], v[146:149], v[198:201], v[38:41]
	v_mfma_f32_16x16x32_bf16 v[38:41], v[150:153], v[214:217], v[38:41]
	v_mfma_f32_16x16x32_bf16 v[34:37], v[158:161], v[198:201], v[34:37]
	v_mfma_f32_16x16x32_bf16 v[34:37], v[182:185], v[214:217], v[34:37]
	v_mfma_f32_16x16x32_bf16 v[22:25], v[146:149], v[218:221], v[22:25]
	v_mfma_f32_16x16x32_bf16 v[22:25], v[150:153], v[222:225], v[22:25]
	v_mfma_f32_16x16x32_bf16 v[18:21], v[158:161], v[218:221], v[18:21]
	v_mfma_f32_16x16x32_bf16 v[18:21], v[182:185], v[222:225], v[18:21]
	v_mfma_f32_16x16x32_bf16 v[6:9], v[146:149], v[226:229], v[6:9]
	v_mfma_f32_16x16x32_bf16 v[6:9], v[150:153], v[230:233], v[6:9]
	v_mfma_f32_16x16x32_bf16 v[2:5], v[158:161], v[226:229], v[2:5]
	v_mfma_f32_16x16x32_bf16 v[2:5], v[182:185], v[230:233], v[2:5]
	s_barrier
	s_add_i32 s20, 0, 0x18000
	s_add_i32 s21, 0, 0x1c000
	v_add_u32_e32 v134, s20, v191
	v_add_u32_e32 v182, s21, v191
	ds_read_b128 v[114:117], v134
	ds_read_b128 v[126:129], v134 offset:1024
	ds_read_b128 v[130:133], v134 offset:2048
	ds_read_b128 v[134:137], v134 offset:3072
	ds_read_b128 v[146:149], v182
	ds_read_b128 v[150:153], v182 offset:1024
	ds_read_b128 v[158:161], v182 offset:2048
	ds_read_b128 v[182:185], v182 offset:3072
	ds_read_b128 v[186:189], v193 offset:32768
	ds_read_b128 v[194:197], v193 offset:33792
	ds_read_b128 v[198:201], v193 offset:34816
	ds_read_b128 v[214:217], v193 offset:35840
	ds_read_b128 v[218:221], v193 offset:36864
	ds_read_b128 v[222:225], v193 offset:37888
	ds_read_b128 v[226:229], v193 offset:38912
	ds_read_b128 v[230:233], v193 offset:39936
	s_mov_b32 m0, s69
	v_lshl_add_u64 v[234:235], v[202:203], 0, s[12:13]
	global_load_lds_dwordx4 v[234:235], off
	v_lshl_add_u64 v[234:235], v[202:203], 0, s[86:87]
	s_mov_b32 m0, s76
	s_nop 0
	global_load_lds_dwordx4 v[234:235], off
	s_waitcnt vmcnt(8)
	s_waitcnt lgkmcnt(0)
	s_barrier
	s_waitcnt lgkmcnt(0)
	v_mfma_f32_16x16x32_bf16 v[142:145], v[114:117], v[186:189], v[142:145]
	v_mfma_f32_16x16x32_bf16 v[142:145], v[126:129], v[194:197], v[142:145]
	v_mfma_f32_16x16x32_bf16 v[138:141], v[130:133], v[186:189], v[138:141]
	v_mfma_f32_16x16x32_bf16 v[138:141], v[134:137], v[194:197], v[138:141]
	v_mfma_f32_16x16x32_bf16 v[110:113], v[114:117], v[198:201], v[110:113]
	v_mfma_f32_16x16x32_bf16 v[110:113], v[126:129], v[214:217], v[110:113]
	v_mfma_f32_16x16x32_bf16 v[106:109], v[130:133], v[198:201], v[106:109]
	v_mfma_f32_16x16x32_bf16 v[106:109], v[134:137], v[214:217], v[106:109]
	v_mfma_f32_16x16x32_bf16 v[94:97], v[114:117], v[218:221], v[94:97]
	v_mfma_f32_16x16x32_bf16 v[94:97], v[126:129], v[222:225], v[94:97]
	v_mfma_f32_16x16x32_bf16 v[90:93], v[130:133], v[218:221], v[90:93]
	v_mfma_f32_16x16x32_bf16 v[90:93], v[134:137], v[222:225], v[90:93]
	v_mfma_f32_16x16x32_bf16 v[78:81], v[114:117], v[226:229], v[78:81]
	v_mfma_f32_16x16x32_bf16 v[78:81], v[126:129], v[230:233], v[78:81]
	v_mfma_f32_16x16x32_bf16 v[74:77], v[130:133], v[226:229], v[74:77]
	v_mfma_f32_16x16x32_bf16 v[74:77], v[134:137], v[230:233], v[74:77]
	v_mfma_f32_16x16x32_bf16 v[122:125], v[146:149], v[186:189], v[122:125]
	v_mfma_f32_16x16x32_bf16 v[122:125], v[150:153], v[194:197], v[122:125]
	v_mfma_f32_16x16x32_bf16 v[118:121], v[158:161], v[186:189], v[118:121]
	v_mfma_f32_16x16x32_bf16 v[118:121], v[182:185], v[194:197], v[118:121]
	v_mfma_f32_16x16x32_bf16 v[102:105], v[146:149], v[198:201], v[102:105]
	v_mfma_f32_16x16x32_bf16 v[102:105], v[150:153], v[214:217], v[102:105]
	v_mfma_f32_16x16x32_bf16 v[98:101], v[158:161], v[198:201], v[98:101]
	v_mfma_f32_16x16x32_bf16 v[98:101], v[182:185], v[214:217], v[98:101]
	v_mfma_f32_16x16x32_bf16 v[86:89], v[146:149], v[218:221], v[86:89]
	v_mfma_f32_16x16x32_bf16 v[86:89], v[150:153], v[222:225], v[86:89]
	v_mfma_f32_16x16x32_bf16 v[82:85], v[158:161], v[218:221], v[82:85]
	v_mfma_f32_16x16x32_bf16 v[82:85], v[182:185], v[222:225], v[82:85]
	v_mfma_f32_16x16x32_bf16 v[70:73], v[146:149], v[226:229], v[70:73]
	v_mfma_f32_16x16x32_bf16 v[70:73], v[150:153], v[230:233], v[70:73]
	v_mfma_f32_16x16x32_bf16 v[66:69], v[158:161], v[226:229], v[66:69]
	v_mfma_f32_16x16x32_bf16 v[66:69], v[182:185], v[230:233], v[66:69]
	s_barrier
	ds_read_b128 v[186:189], v193 offset:49152
	ds_read_b128 v[194:197], v193 offset:50176
	ds_read_b128 v[198:201], v193 offset:51200
	ds_read_b128 v[214:217], v193 offset:52224
	ds_read_b128 v[218:221], v193 offset:53248
	ds_read_b128 v[222:225], v193 offset:54272
	ds_read_b128 v[226:229], v193 offset:55296
	ds_read_b128 v[230:233], v193 offset:56320
	s_add_i32 s20, s20, s46
	s_mov_b32 m0, s20
	v_lshl_add_u64 v[234:235], v[162:163], 0, s[34:35]
	global_load_lds_dwordx4 v[234:235], off
	v_lshl_add_u64 v[234:235], v[162:163], 0, s[96:97]
	s_add_i32 m0, s20, 0x2000
	s_add_i32 s20, s21, s46
	global_load_lds_dwordx4 v[234:235], off
	v_lshl_add_u64 v[234:235], v[162:163], 0, vcc
	s_mov_b32 m0, s20
	v_lshl_add_u64 v[162:163], v[162:163], 0, s[0:1]
	global_load_lds_dwordx4 v[234:235], off
	s_add_i32 m0, s20, 0x2000
	s_nop 0
	global_load_lds_dwordx4 v[162:163], off
	v_lshl_add_u64 v[162:163], v[202:203], 0, s[34:35]
	s_mov_b32 m0, s77
	s_nop 0
	global_load_lds_dwordx4 v[162:163], off
	v_lshl_add_u64 v[162:163], v[202:203], 0, s[96:97]
	s_mov_b32 m0, s78
	s_nop 0
	global_load_lds_dwordx4 v[162:163], off
	s_waitcnt vmcnt(8)
	s_waitcnt lgkmcnt(0)
	s_barrier
	s_waitcnt lgkmcnt(0)
	v_mfma_f32_16x16x32_bf16 v[62:65], v[114:117], v[186:189], v[62:65]
	v_mfma_f32_16x16x32_bf16 v[62:65], v[126:129], v[194:197], v[62:65]
	v_mfma_f32_16x16x32_bf16 v[58:61], v[130:133], v[186:189], v[58:61]
	v_mfma_f32_16x16x32_bf16 v[58:61], v[134:137], v[194:197], v[58:61]
	v_mfma_f32_16x16x32_bf16 v[46:49], v[114:117], v[198:201], v[46:49]
	v_mfma_f32_16x16x32_bf16 v[46:49], v[126:129], v[214:217], v[46:49]
	v_mfma_f32_16x16x32_bf16 v[42:45], v[130:133], v[198:201], v[42:45]
	v_mfma_f32_16x16x32_bf16 v[42:45], v[134:137], v[214:217], v[42:45]
	v_mfma_f32_16x16x32_bf16 v[30:33], v[114:117], v[218:221], v[30:33]
	v_mfma_f32_16x16x32_bf16 v[30:33], v[126:129], v[222:225], v[30:33]
	v_mfma_f32_16x16x32_bf16 v[26:29], v[130:133], v[218:221], v[26:29]
	v_mfma_f32_16x16x32_bf16 v[26:29], v[134:137], v[222:225], v[26:29]
	v_mfma_f32_16x16x32_bf16 v[14:17], v[114:117], v[226:229], v[14:17]
	v_mfma_f32_16x16x32_bf16 v[14:17], v[126:129], v[230:233], v[14:17]
	v_mfma_f32_16x16x32_bf16 v[10:13], v[130:133], v[226:229], v[10:13]
	v_mfma_f32_16x16x32_bf16 v[10:13], v[134:137], v[230:233], v[10:13]
	s_add_i32 s84, s84, 2
	s_add_u32 s56, s56, 0x100
	s_addc_u32 s57, s57, 0
	s_add_u32 s62, s62, 0x100
	s_addc_u32 s63, s63, 0
	v_mfma_f32_16x16x32_bf16 v[54:57], v[146:149], v[186:189], v[54:57]
	v_mfma_f32_16x16x32_bf16 v[54:57], v[150:153], v[194:197], v[54:57]
	v_mfma_f32_16x16x32_bf16 v[50:53], v[158:161], v[186:189], v[50:53]
	v_mfma_f32_16x16x32_bf16 v[50:53], v[182:185], v[194:197], v[50:53]
	v_mfma_f32_16x16x32_bf16 v[38:41], v[146:149], v[198:201], v[38:41]
	v_mfma_f32_16x16x32_bf16 v[38:41], v[150:153], v[214:217], v[38:41]
	v_mfma_f32_16x16x32_bf16 v[34:37], v[158:161], v[198:201], v[34:37]
	v_mfma_f32_16x16x32_bf16 v[34:37], v[182:185], v[214:217], v[34:37]
	v_mfma_f32_16x16x32_bf16 v[22:25], v[146:149], v[218:221], v[22:25]
	v_mfma_f32_16x16x32_bf16 v[22:25], v[150:153], v[222:225], v[22:25]
	v_mfma_f32_16x16x32_bf16 v[18:21], v[158:161], v[218:221], v[18:21]
	v_mfma_f32_16x16x32_bf16 v[18:21], v[182:185], v[222:225], v[18:21]
	v_mfma_f32_16x16x32_bf16 v[6:9], v[146:149], v[226:229], v[6:9]
	v_mfma_f32_16x16x32_bf16 v[6:9], v[150:153], v[230:233], v[6:9]
	v_mfma_f32_16x16x32_bf16 v[2:5], v[158:161], v[226:229], v[2:5]
	v_mfma_f32_16x16x32_bf16 v[2:5], v[182:185], v[230:233], v[2:5]
	s_barrier
	s_cmp_gt_u32 s84, 41
	s_cbranch_scc0 .LBB0_446
	s_setprio 0
	s_cmp_eq_u64 s[40:41], 0
	s_cbranch_scc1 .Lpx_446
	s_setprio 1
.Lpx_446:
	s_and_b64 vcc, exec, s[40:41]
	s_cbranch_vccz .LBB0_449
	s_barrier
.LBB0_449:
	v_lshl_or_b32 v158, s90, 8, v192
	v_lshl_add_u32 v188, s91, 8, v190
	v_ashrrev_i32_e32 v159, 31, v158
	v_lshlrev_b64 v[202:203], 1, v[158:159]
	v_ashrrev_i32_e32 v189, 31, v188
	v_lshl_add_u64 v[160:161], s[94:95], 0, v[202:203]
	v_lshlrev_b64 v[162:163], 11, v[188:189]
	v_lshl_add_u64 v[114:115], v[160:161], 0, v[162:163]
	global_load_dwordx4 v[194:197], v[114:115], off
	global_load_dwordx4 v[198:201], v[114:115], off offset:256
	v_or_b32_e32 v114, 16, v188
	v_ashrrev_i32_e32 v115, 31, v114
	v_lshlrev_b64 v[186:187], 11, v[114:115]
	v_lshl_add_u64 v[114:115], v[160:161], 0, v[186:187]
	global_load_dwordx4 v[150:153], v[114:115], off
	global_load_dwordx4 v[146:149], v[114:115], off offset:256
	v_or_b32_e32 v114, 32, v188
	v_ashrrev_i32_e32 v115, 31, v114
	v_lshlrev_b64 v[184:185], 11, v[114:115]
	v_lshl_add_u64 v[114:115], v[160:161], 0, v[184:185]
	global_load_dwordx4 v[134:137], v[114:115], off
	global_load_dwordx4 v[130:133], v[114:115], off offset:256
	v_or_b32_e32 v114, 48, v188
	v_ashrrev_i32_e32 v115, 31, v114
	v_lshlrev_b64 v[182:183], 11, v[114:115]
	v_lshl_add_u64 v[114:115], v[160:161], 0, v[182:183]
	global_load_dwordx4 v[126:129], v[114:115], off
	s_nop 0
	global_load_dwordx4 v[114:117], v[114:115], off offset:256
	s_waitcnt vmcnt(0)
	v_lshlrev_b32_e32 v214, 16, v194
	v_add_f32_e32 v214, v142, v214
	v_and_b32_e32 v142, 0xffff0000, v194
	v_add_f32_e32 v194, v143, v142
	v_lshlrev_b32_e32 v142, 16, v195
	v_add_f32_e32 v144, v144, v142
	v_and_b32_e32 v142, 0xffff0000, v195
	v_add_f32_e32 v145, v145, v142
	v_lshlrev_b32_e32 v142, 16, v196
	v_add_f32_e32 v195, v138, v142
	v_and_b32_e32 v138, 0xffff0000, v196
	v_add_f32_e32 v196, v139, v138
	v_lshlrev_b32_e32 v138, 16, v197
	v_add_f32_e32 v215, v140, v138
	v_and_b32_e32 v138, 0xffff0000, v197
	v_lshl_add_u64 v[142:143], s[94:95], 0, v[162:163]
	v_add_f32_e32 v197, v141, v138
	v_cvt_pk_bf16_f32 v138, v214, v194
	v_lshl_add_u64 v[142:143], v[142:143], 0, v[202:203]
	v_cvt_pk_bf16_f32 v139, v144, v145
	v_cvt_pk_bf16_f32 v140, v195, v196
	v_cvt_pk_bf16_f32 v141, v215, v197
	global_store_dwordx4 v[142:143], v[138:141], off
	s_nop 1
	v_mul_f32_e32 v138, v194, v194
	v_fmac_f32_e32 v138, v214, v214
	v_fmac_f32_e32 v138, v144, v144
	v_lshlrev_b32_e32 v139, 16, v198
	v_fmac_f32_e32 v138, v145, v145
	v_add_f32_e32 v122, v122, v139
	v_and_b32_e32 v139, 0xffff0000, v198
	v_fmac_f32_e32 v138, v195, v195
	v_add_f32_e32 v123, v123, v139
	v_lshlrev_b32_e32 v139, 16, v199
	v_fmac_f32_e32 v138, v196, v196
	v_add_f32_e32 v124, v124, v139
	v_and_b32_e32 v139, 0xffff0000, v199
	v_fmac_f32_e32 v138, v215, v215
	v_add_f32_e32 v125, v125, v139
	v_lshlrev_b32_e32 v139, 16, v200
	v_fmac_f32_e32 v138, v197, v197
	v_add_f32_e32 v139, v118, v139
	v_and_b32_e32 v118, 0xffff0000, v200
	v_add_f32_e32 v140, v119, v118
	v_lshlrev_b32_e32 v118, 16, v201
	v_fmac_f32_e32 v138, v122, v122
	v_add_f32_e32 v141, v120, v118
	v_and_b32_e32 v118, 0xffff0000, v201
	v_fmac_f32_e32 v138, v123, v123
	v_add_f32_e32 v144, v121, v118
	v_cvt_pk_bf16_f32 v118, v122, v123
	v_cvt_pk_bf16_f32 v119, v124, v125
	v_fmac_f32_e32 v138, v124, v124
	v_cvt_pk_bf16_f32 v120, v139, v140
	v_cvt_pk_bf16_f32 v121, v141, v144
	global_store_dwordx4 v[142:143], v[118:121], off offset:256
	v_fmac_f32_e32 v138, v125, v125
	v_fmac_f32_e32 v138, v139, v139
	v_and_b32_e32 v119, 64, v206
	v_xor_b32_e32 v118, 16, v206
	v_add_u32_e32 v119, 64, v119
	v_fmac_f32_e32 v138, v140, v140
	v_cmp_lt_i32_e32 vcc, v118, v119
	v_fmac_f32_e32 v138, v141, v141
	v_fmac_f32_e32 v138, v144, v144
	v_cndmask_b32_e32 v118, v206, v118, vcc
	v_lshlrev_b32_e32 v120, 2, v118
	ds_bpermute_b32 v118, v120, v138
	s_waitcnt lgkmcnt(0)
	v_add_f32_e32 v122, v138, v118
	v_xor_b32_e32 v118, 32, v206
	v_cmp_lt_i32_e32 vcc, v118, v119
	s_nop 1
	v_cndmask_b32_e32 v118, v206, v118, vcc
	v_lshlrev_b32_e32 v121, 2, v118
	ds_bpermute_b32 v123, v121, v122
	v_lshl_add_u64 v[118:119], v[188:189], 3, s[6:7]
	s_and_saveexec_b64 s[56:57], s[52:53]
	s_mov_b64 s[86:87], 0x30080
	s_cbranch_execz .LBB0_451
	s_waitcnt lgkmcnt(0)
	v_add_f32_e32 v122, v122, v123
	v_mul_f32_e32 v122, 0x4d800000, v122
	v_trunc_f32_e32 v122, v122
	v_mul_f32_e32 v123, 0x2f800000, v122
	v_floor_f32_e32 v123, v123
	v_fmac_f32_e32 v122, 0xcf800000, v123
	v_cvt_u32_f32_e32 v122, v122
	v_cvt_u32_f32_e32 v123, v123
	global_atomic_add_x2 v[118:119], v[122:123], off

.LBB0_487:
	s_ashr_i32 s57, s56, 31
	s_lshl_b64 s[20:21], s[56:57], 19
	s_add_u32 s60, s94, s20
	s_addc_u32 s61, s95, s21
	s_and_b64 s[20:21], s[54:55], exec
	s_cselect_b32 s57, s61, s69
	s_cselect_b32 s86, s60, s68
	s_ashr_i32 s51, s50, 31
	s_lshl_b64 s[20:21], s[50:51], 19
	s_add_u32 s62, s15, s20
	s_addc_u32 s63, s42, s21
	s_and_b64 s[20:21], s[54:55], exec
	s_cselect_b32 s51, s63, s77
	s_cselect_b32 s87, s62, s76
	s_add_u32 s68, s68, 0x40080
	s_addc_u32 s69, s69, 0
	s_add_u32 s91, s76, 0x100
	v_mov_b32_e32 v2, 0
	s_addc_u32 s96, s77, 0
	s_mov_b32 s97, -2
	s_add_i32 s22, 0, 0x10000
	v_add_u32_e32 v152, s22, v139
	s_add_i32 s23, 0, 0x14000
	ds_read_b128 v[134:137], v152
	ds_read_b128 v[144:147], v152 offset:1024
	ds_read_b128 v[148:151], v152 offset:2048
	ds_read_b128 v[152:155], v152 offset:3072
	v_add_u32_e32 v186, s23, v139
	ds_read_b128 v[156:159], v186
	ds_read_b128 v[160:163], v186 offset:1024
	ds_read_b128 v[182:185], v186 offset:2048
	ds_read_b128 v[186:189], v186 offset:3072
	ds_read_b128 v[190:193], v142
	ds_read_b128 v[194:197], v142 offset:1024
	ds_read_b128 v[198:201], v142 offset:2048
	ds_read_b128 v[214:217], v142 offset:3072
	ds_read_b128 v[218:221], v142 offset:4096
	ds_read_b128 v[222:225], v142 offset:5120
	ds_read_b128 v[226:229], v142 offset:6144
	ds_read_b128 v[230:233], v142 offset:7168
	s_setprio 0
	s_cmp_eq_u64 s[48:49], 0
	s_cbranch_scc0 .Lpr_488
	s_setprio 1

.LBB0_488:
	s_add_i32 s22, 0, 0x10000
	v_add_u32_e32 v143, s22, v139
	s_add_i32 s23, 0, 0x14000
	ds_read_b128 v[134:137], v143
	ds_read_b128 v[144:147], v143 offset:1024
	ds_read_b128 v[148:151], v143 offset:2048
	ds_read_b128 v[152:155], v143 offset:3072
	v_add_u32_e32 v143, s23, v139
	ds_read_b128 v[156:159], v143
	ds_read_b128 v[160:163], v143 offset:1024
	ds_read_b128 v[182:185], v143 offset:2048
	ds_read_b128 v[186:189], v143 offset:3072
	ds_read_b128 v[190:193], v142
	ds_read_b128 v[194:197], v142 offset:1024
	ds_read_b128 v[198:201], v142 offset:2048
	ds_read_b128 v[214:217], v142 offset:3072
	ds_read_b128 v[218:221], v142 offset:4096
	ds_read_b128 v[222:225], v142 offset:5120
	ds_read_b128 v[226:229], v142 offset:6144
	ds_read_b128 v[230:233], v142 offset:7168
	s_add_u32 s20, s68, 0xfffc0080
	s_addc_u32 s21, s69, -1
	s_cmp_eq_u32 s97, 12
	s_cselect_b32 s77, s57, s21
	s_cselect_b32 s76, s86, s20
	s_cselect_b32 s21, s51, s96
	s_cselect_b32 s20, s87, s91
	s_add_i32 m0, s43, 0xc000
	v_lshl_add_u64 v[202:203], s[68:69], 0, v[132:133]
	global_load_lds_dwordx4 v[202:203], off
	v_lshl_add_u64 v[202:203], v[202:203], 0, s[72:73]
	s_add_i32 m0, s43, 0xe000
	s_nop 0
	global_load_lds_dwordx4 v[202:203], off
	s_waitcnt vmcnt(8)
	s_waitcnt lgkmcnt(0)
	s_barrier
	s_waitcnt lgkmcnt(0)
	v_mfma_f32_16x16x32_bf16 v[126:129], v[134:137], v[190:193], v[126:129]
	v_mfma_f32_16x16x32_bf16 v[126:129], v[144:147], v[194:197], v[126:129]
	v_mfma_f32_16x16x32_bf16 v[114:117], v[148:151], v[190:193], v[114:117]
	v_mfma_f32_16x16x32_bf16 v[114:117], v[152:155], v[194:197], v[114:117]
	v_mfma_f32_16x16x32_bf16 v[110:113], v[134:137], v[198:201], v[110:113]
	v_mfma_f32_16x16x32_bf16 v[110:113], v[144:147], v[214:217], v[110:113]
	v_mfma_f32_16x16x32_bf16 v[98:101], v[148:151], v[198:201], v[98:101]
	v_mfma_f32_16x16x32_bf16 v[98:101], v[152:155], v[214:217], v[98:101]
	v_mfma_f32_16x16x32_bf16 v[94:97], v[134:137], v[218:221], v[94:97]
	v_mfma_f32_16x16x32_bf16 v[94:97], v[144:147], v[222:225], v[94:97]
	v_mfma_f32_16x16x32_bf16 v[82:85], v[148:151], v[218:221], v[82:85]
	v_mfma_f32_16x16x32_bf16 v[82:85], v[152:155], v[222:225], v[82:85]
	v_mfma_f32_16x16x32_bf16 v[78:81], v[134:137], v[226:229], v[78:81]
	v_mfma_f32_16x16x32_bf16 v[78:81], v[144:147], v[230:233], v[78:81]
	v_mfma_f32_16x16x32_bf16 v[66:69], v[148:151], v[226:229], v[66:69]
	v_mfma_f32_16x16x32_bf16 v[66:69], v[152:155], v[230:233], v[66:69]
	v_mfma_f32_16x16x32_bf16 v[122:125], v[156:159], v[190:193], v[122:125]
	v_mfma_f32_16x16x32_bf16 v[122:125], v[160:163], v[194:197], v[122:125]
	v_mfma_f32_16x16x32_bf16 v[118:121], v[182:185], v[190:193], v[118:121]
	v_mfma_f32_16x16x32_bf16 v[118:121], v[186:189], v[194:197], v[118:121]
	v_mfma_f32_16x16x32_bf16 v[106:109], v[156:159], v[198:201], v[106:109]
	v_mfma_f32_16x16x32_bf16 v[106:109], v[160:163], v[214:217], v[106:109]
	v_mfma_f32_16x16x32_bf16 v[102:105], v[182:185], v[198:201], v[102:105]
	v_mfma_f32_16x16x32_bf16 v[102:105], v[186:189], v[214:217], v[102:105]
	v_mfma_f32_16x16x32_bf16 v[90:93], v[156:159], v[218:221], v[90:93]
	v_mfma_f32_16x16x32_bf16 v[90:93], v[160:163], v[222:225], v[90:93]
	v_mfma_f32_16x16x32_bf16 v[86:89], v[182:185], v[218:221], v[86:89]
	v_mfma_f32_16x16x32_bf16 v[86:89], v[186:189], v[222:225], v[86:89]
	v_mfma_f32_16x16x32_bf16 v[74:77], v[156:159], v[226:229], v[74:77]
	v_mfma_f32_16x16x32_bf16 v[74:77], v[160:163], v[230:233], v[74:77]
	v_mfma_f32_16x16x32_bf16 v[70:73], v[182:185], v[226:229], v[70:73]
	v_mfma_f32_16x16x32_bf16 v[70:73], v[186:189], v[230:233], v[70:73]
	s_barrier
	ds_read_b128 v[190:193], v142 offset:16384
	ds_read_b128 v[194:197], v142 offset:17408
	ds_read_b128 v[198:201], v142 offset:18432
	ds_read_b128 v[214:217], v142 offset:19456
	ds_read_b128 v[218:221], v142 offset:20480
	ds_read_b128 v[222:225], v142 offset:21504
	ds_read_b128 v[226:229], v142 offset:22528
	ds_read_b128 v[230:233], v142 offset:23552
	v_lshl_add_u64 v[202:203], s[20:21], 0, v[0:1]
	s_add_i32 s20, s22, s14
	s_mov_b32 m0, s20
	s_nop 0
	s_nop 0
	global_load_lds_dwordx4 v[202:203], off
	v_lshl_add_u64 v[234:235], v[202:203], 0, s[72:73]
	s_add_i32 m0, s20, 0x2000
	s_add_i32 s20, s23, s14
	global_load_lds_dwordx4 v[234:235], off
	v_lshl_add_u64 v[234:235], v[202:203], 0, s[28:29]
	s_mov_b32 m0, s20
	s_nop 0
	global_load_lds_dwordx4 v[234:235], off
	v_lshl_add_u64 v[234:235], v[202:203], 0, s[82:83]
	s_add_i32 m0, s20, 0x2000
	s_nop 0
	global_load_lds_dwordx4 v[234:235], off
	v_lshl_add_u64 v[234:235], s[76:77], 0, v[130:131]
	s_mov_b32 m0, s43
	v_lshl_add_u64 v[236:237], v[234:235], 0, s[72:73]
	global_load_lds_dwordx4 v[234:235], off
	s_mov_b32 m0, s46
	s_nop 0
	global_load_lds_dwordx4 v[236:237], off
	s_waitcnt vmcnt(8)
	s_waitcnt lgkmcnt(0)
	s_barrier
	s_waitcnt lgkmcnt(0)
	v_mfma_f32_16x16x32_bf16 v[62:65], v[134:137], v[190:193], v[62:65]
	v_mfma_f32_16x16x32_bf16 v[62:65], v[144:147], v[194:197], v[62:65]
	v_mfma_f32_16x16x32_bf16 v[50:53], v[148:151], v[190:193], v[50:53]
	v_mfma_f32_16x16x32_bf16 v[50:53], v[152:155], v[194:197], v[50:53]
	v_mfma_f32_16x16x32_bf16 v[46:49], v[134:137], v[198:201], v[46:49]
	v_mfma_f32_16x16x32_bf16 v[46:49], v[144:147], v[214:217], v[46:49]
	v_mfma_f32_16x16x32_bf16 v[34:37], v[148:151], v[198:201], v[34:37]
	v_mfma_f32_16x16x32_bf16 v[34:37], v[152:155], v[214:217], v[34:37]
	v_mfma_f32_16x16x32_bf16 v[30:33], v[134:137], v[218:221], v[30:33]
	v_mfma_f32_16x16x32_bf16 v[30:33], v[144:147], v[222:225], v[30:33]
	v_mfma_f32_16x16x32_bf16 v[18:21], v[148:151], v[218:221], v[18:21]
	v_mfma_f32_16x16x32_bf16 v[18:21], v[152:155], v[222:225], v[18:21]
	v_mfma_f32_16x16x32_bf16 v[14:17], v[134:137], v[226:229], v[14:17]
	v_mfma_f32_16x16x32_bf16 v[14:17], v[144:147], v[230:233], v[14:17]
	v_mfma_f32_16x16x32_bf16 v[6:9], v[148:151], v[226:229], v[6:9]
	v_mfma_f32_16x16x32_bf16 v[6:9], v[152:155], v[230:233], v[6:9]
	v_mfma_f32_16x16x32_bf16 v[58:61], v[156:159], v[190:193], v[58:61]
	v_mfma_f32_16x16x32_bf16 v[58:61], v[160:163], v[194:197], v[58:61]
	v_mfma_f32_16x16x32_bf16 v[54:57], v[182:185], v[190:193], v[54:57]
	v_mfma_f32_16x16x32_bf16 v[54:57], v[186:189], v[194:197], v[54:57]
	v_mfma_f32_16x16x32_bf16 v[42:45], v[156:159], v[198:201], v[42:45]
	v_mfma_f32_16x16x32_bf16 v[42:45], v[160:163], v[214:217], v[42:45]
	v_mfma_f32_16x16x32_bf16 v[38:41], v[182:185], v[198:201], v[38:41]
	v_mfma_f32_16x16x32_bf16 v[38:41], v[186:189], v[214:217], v[38:41]
	v_mfma_f32_16x16x32_bf16 v[26:29], v[156:159], v[218:221], v[26:29]
	v_mfma_f32_16x16x32_bf16 v[26:29], v[160:163], v[222:225], v[26:29]
	v_mfma_f32_16x16x32_bf16 v[22:25], v[182:185], v[218:221], v[22:25]
	v_mfma_f32_16x16x32_bf16 v[22:25], v[186:189], v[222:225], v[22:25]
	v_mfma_f32_16x16x32_bf16 v[10:13], v[156:159], v[226:229], v[10:13]
	v_mfma_f32_16x16x32_bf16 v[10:13], v[160:163], v[230:233], v[10:13]
	v_mfma_f32_16x16x32_bf16 v[2:5], v[182:185], v[226:229], v[2:5]
	v_mfma_f32_16x16x32_bf16 v[2:5], v[186:189], v[230:233], v[2:5]
	s_barrier
	s_add_i32 s20, 0, 0x18000
	v_add_u32_e32 v143, s20, v139
	s_add_i32 s21, 0, 0x1c000
	ds_read_b128 v[134:137], v143
	ds_read_b128 v[144:147], v143 offset:1024
	ds_read_b128 v[148:151], v143 offset:2048
	ds_read_b128 v[152:155], v143 offset:3072
	v_add_u32_e32 v143, s21, v139
	ds_read_b128 v[156:159], v143
	ds_read_b128 v[160:163], v143 offset:1024
	ds_read_b128 v[182:185], v143 offset:2048
	ds_read_b128 v[186:189], v143 offset:3072
	ds_read_b128 v[190:193], v142 offset:32768
	ds_read_b128 v[194:197], v142 offset:33792
	ds_read_b128 v[198:201], v142 offset:34816
	ds_read_b128 v[214:217], v142 offset:35840
	ds_read_b128 v[218:221], v142 offset:36864
	ds_read_b128 v[222:225], v142 offset:37888
	ds_read_b128 v[226:229], v142 offset:38912
	ds_read_b128 v[230:233], v142 offset:39936
	s_mov_b32 m0, s47
	v_lshl_add_u64 v[236:237], v[234:235], 0, s[28:29]
	global_load_lds_dwordx4 v[236:237], off
	v_lshl_add_u64 v[236:237], v[234:235], 0, s[82:83]
	s_mov_b32 m0, s78
	s_nop 0
	global_load_lds_dwordx4 v[236:237], off
	s_waitcnt vmcnt(8)
	s_waitcnt lgkmcnt(0)
	s_barrier
	s_waitcnt lgkmcnt(0)
	v_mfma_f32_16x16x32_bf16 v[126:129], v[134:137], v[190:193], v[126:129]
	v_mfma_f32_16x16x32_bf16 v[126:129], v[144:147], v[194:197], v[126:129]
	v_mfma_f32_16x16x32_bf16 v[114:117], v[148:151], v[190:193], v[114:117]
	v_mfma_f32_16x16x32_bf16 v[114:117], v[152:155], v[194:197], v[114:117]
	v_mfma_f32_16x16x32_bf16 v[110:113], v[134:137], v[198:201], v[110:113]
	v_mfma_f32_16x16x32_bf16 v[110:113], v[144:147], v[214:217], v[110:113]
	v_mfma_f32_16x16x32_bf16 v[98:101], v[148:151], v[198:201], v[98:101]
	v_mfma_f32_16x16x32_bf16 v[98:101], v[152:155], v[214:217], v[98:101]
	v_mfma_f32_16x16x32_bf16 v[94:97], v[134:137], v[218:221], v[94:97]
	v_mfma_f32_16x16x32_bf16 v[94:97], v[144:147], v[222:225], v[94:97]
	v_mfma_f32_16x16x32_bf16 v[82:85], v[148:151], v[218:221], v[82:85]
	v_mfma_f32_16x16x32_bf16 v[82:85], v[152:155], v[222:225], v[82:85]
	v_mfma_f32_16x16x32_bf16 v[78:81], v[134:137], v[226:229], v[78:81]
	v_mfma_f32_16x16x32_bf16 v[78:81], v[144:147], v[230:233], v[78:81]
	v_mfma_f32_16x16x32_bf16 v[66:69], v[148:151], v[226:229], v[66:69]
	v_mfma_f32_16x16x32_bf16 v[66:69], v[152:155], v[230:233], v[66:69]
	v_mfma_f32_16x16x32_bf16 v[122:125], v[156:159], v[190:193], v[122:125]
	v_mfma_f32_16x16x32_bf16 v[122:125], v[160:163], v[194:197], v[122:125]
	v_mfma_f32_16x16x32_bf16 v[118:121], v[182:185], v[190:193], v[118:121]
	v_mfma_f32_16x16x32_bf16 v[118:121], v[186:189], v[194:197], v[118:121]
	v_mfma_f32_16x16x32_bf16 v[106:109], v[156:159], v[198:201], v[106:109]
	v_mfma_f32_16x16x32_bf16 v[106:109], v[160:163], v[214:217], v[106:109]
	v_mfma_f32_16x16x32_bf16 v[102:105], v[182:185], v[198:201], v[102:105]
	v_mfma_f32_16x16x32_bf16 v[102:105], v[186:189], v[214:217], v[102:105]
	v_mfma_f32_16x16x32_bf16 v[90:93], v[156:159], v[218:221], v[90:93]
	v_mfma_f32_16x16x32_bf16 v[90:93], v[160:163], v[222:225], v[90:93]
	v_mfma_f32_16x16x32_bf16 v[86:89], v[182:185], v[218:221], v[86:89]
	v_mfma_f32_16x16x32_bf16 v[86:89], v[186:189], v[222:225], v[86:89]
	v_mfma_f32_16x16x32_bf16 v[74:77], v[156:159], v[226:229], v[74:77]
	v_mfma_f32_16x16x32_bf16 v[74:77], v[160:163], v[230:233], v[74:77]
	v_mfma_f32_16x16x32_bf16 v[70:73], v[182:185], v[226:229], v[70:73]
	v_mfma_f32_16x16x32_bf16 v[70:73], v[186:189], v[230:233], v[70:73]
	s_barrier
	ds_read_b128 v[190:193], v142 offset:49152
	ds_read_b128 v[194:197], v142 offset:50176
	ds_read_b128 v[198:201], v142 offset:51200
	ds_read_b128 v[214:217], v142 offset:52224
	ds_read_b128 v[218:221], v142 offset:53248
	ds_read_b128 v[222:225], v142 offset:54272
	ds_read_b128 v[226:229], v142 offset:55296
	ds_read_b128 v[230:233], v142 offset:56320
	s_add_i32 s20, s20, s14
	s_mov_b32 m0, s20
	v_lshl_add_u64 v[236:237], v[202:203], 0, s[34:35]
	global_load_lds_dwordx4 v[236:237], off
	v_lshl_add_u64 v[236:237], v[202:203], 0, s[38:39]
	s_add_i32 m0, s20, 0x2000
	s_add_i32 s20, s21, s14
	global_load_lds_dwordx4 v[236:237], off
	v_lshl_add_u64 v[236:237], v[202:203], 0, s[44:45]
	s_mov_b32 m0, s20
	v_lshl_add_u64 v[202:203], v[202:203], 0, s[10:11]
	global_load_lds_dwordx4 v[236:237], off
	s_add_i32 m0, s20, 0x2000
	s_nop 0
	global_load_lds_dwordx4 v[202:203], off
	v_lshl_add_u64 v[202:203], v[234:235], 0, s[34:35]
	s_mov_b32 m0, s79
	s_nop 0
	global_load_lds_dwordx4 v[202:203], off
	v_lshl_add_u64 v[202:203], v[234:235], 0, s[38:39]
	s_mov_b32 m0, s88
	s_nop 0
	global_load_lds_dwordx4 v[202:203], off
	s_waitcnt vmcnt(8)
	s_waitcnt lgkmcnt(0)
	s_barrier
	s_waitcnt lgkmcnt(0)
	v_mfma_f32_16x16x32_bf16 v[62:65], v[134:137], v[190:193], v[62:65]
	v_mfma_f32_16x16x32_bf16 v[62:65], v[144:147], v[194:197], v[62:65]
	v_mfma_f32_16x16x32_bf16 v[50:53], v[148:151], v[190:193], v[50:53]
	v_mfma_f32_16x16x32_bf16 v[50:53], v[152:155], v[194:197], v[50:53]
	v_mfma_f32_16x16x32_bf16 v[46:49], v[134:137], v[198:201], v[46:49]
	v_mfma_f32_16x16x32_bf16 v[46:49], v[144:147], v[214:217], v[46:49]
	v_mfma_f32_16x16x32_bf16 v[34:37], v[148:151], v[198:201], v[34:37]
	v_mfma_f32_16x16x32_bf16 v[34:37], v[152:155], v[214:217], v[34:37]
	v_mfma_f32_16x16x32_bf16 v[30:33], v[134:137], v[218:221], v[30:33]
	v_mfma_f32_16x16x32_bf16 v[30:33], v[144:147], v[222:225], v[30:33]
	v_mfma_f32_16x16x32_bf16 v[18:21], v[148:151], v[218:221], v[18:21]
	v_mfma_f32_16x16x32_bf16 v[18:21], v[152:155], v[222:225], v[18:21]
	v_mfma_f32_16x16x32_bf16 v[14:17], v[134:137], v[226:229], v[14:17]
	v_mfma_f32_16x16x32_bf16 v[14:17], v[144:147], v[230:233], v[14:17]
	v_mfma_f32_16x16x32_bf16 v[6:9], v[148:151], v[226:229], v[6:9]
	v_mfma_f32_16x16x32_bf16 v[6:9], v[152:155], v[230:233], v[6:9]
	s_add_i32 s97, s97, 2
	s_add_u32 s68, s68, 0x100
	s_addc_u32 s69, s69, 0
	s_add_u32 s91, s91, 0x100
	s_addc_u32 s96, s96, 0
	v_mfma_f32_16x16x32_bf16 v[58:61], v[156:159], v[190:193], v[58:61]
	v_mfma_f32_16x16x32_bf16 v[58:61], v[160:163], v[194:197], v[58:61]
	v_mfma_f32_16x16x32_bf16 v[54:57], v[182:185], v[190:193], v[54:57]
	v_mfma_f32_16x16x32_bf16 v[54:57], v[186:189], v[194:197], v[54:57]
	v_mfma_f32_16x16x32_bf16 v[42:45], v[156:159], v[198:201], v[42:45]
	v_mfma_f32_16x16x32_bf16 v[42:45], v[160:163], v[214:217], v[42:45]
	v_mfma_f32_16x16x32_bf16 v[38:41], v[182:185], v[198:201], v[38:41]
	v_mfma_f32_16x16x32_bf16 v[38:41], v[186:189], v[214:217], v[38:41]
	v_mfma_f32_16x16x32_bf16 v[26:29], v[156:159], v[218:221], v[26:29]
	v_mfma_f32_16x16x32_bf16 v[26:29], v[160:163], v[222:225], v[26:29]
	v_mfma_f32_16x16x32_bf16 v[22:25], v[182:185], v[218:221], v[22:25]
	v_mfma_f32_16x16x32_bf16 v[22:25], v[186:189], v[222:225], v[22:25]
	v_mfma_f32_16x16x32_bf16 v[10:13], v[156:159], v[226:229], v[10:13]
	v_mfma_f32_16x16x32_bf16 v[10:13], v[160:163], v[230:233], v[10:13]
	v_mfma_f32_16x16x32_bf16 v[2:5], v[182:185], v[226:229], v[2:5]
	v_mfma_f32_16x16x32_bf16 v[2:5], v[186:189], v[230:233], v[2:5]
	s_barrier
	s_cmp_gt_u32 s97, 13
	s_cbranch_scc0 .LBB0_488
	s_setprio 0
	s_cmp_eq_u64 s[48:49], 0
	s_cbranch_scc1 .Lpx_488
	s_setprio 1
.Lpx_488:
	s_and_b64 vcc, exec, s[48:49]
	s_cbranch_vccz .LBB0_491
	s_barrier

.LBB0_603:
	s_ashr_i32 s51, s50, 31
	s_lshl_b64 s[20:21], s[50:51], 18
	s_add_u32 s78, s0, s20
	s_addc_u32 s79, s1, s21
	s_and_b64 s[20:21], s[56:57], exec
	s_cselect_b32 s42, s79, s7
	s_cselect_b32 s43, s78, s6
	s_ashr_i32 s49, s48, 31
	s_lshl_b64 s[20:21], s[48:49], 18
	s_add_u32 s40, s76, s20
	s_addc_u32 s41, s77, s21
	s_and_b64 s[20:21], s[56:57], exec
	s_cselect_b32 s46, s41, s69
	s_cselect_b32 s47, s40, s68
	s_add_u32 s6, s6, 0x20080
	s_addc_u32 s7, s7, 0
	s_add_u32 s49, s68, 0x100
	v_mov_b32_e32 v2, 0
	s_addc_u32 s51, s69, 0
	s_mov_b32 s84, -2
	s_waitcnt lgkmcnt(0)
	s_add_i32 s22, 0, 0x10000
	s_add_i32 s23, 0, 0x14000
	v_add_u32_e32 v150, s22, v139
	v_add_u32_e32 v186, s23, v139
	ds_read_b128 v[134:137], v150
	ds_read_b128 v[142:145], v150 offset:1024
	ds_read_b128 v[146:149], v150 offset:2048
	ds_read_b128 v[150:153], v150 offset:3072
	ds_read_b128 v[154:157], v186
	ds_read_b128 v[158:161], v186 offset:1024
	ds_read_b128 v[182:185], v186 offset:2048
	ds_read_b128 v[186:189], v186 offset:3072
	ds_read_b128 v[190:193], v141
	ds_read_b128 v[194:197], v141 offset:1024
	ds_read_b128 v[198:201], v141 offset:2048
	ds_read_b128 v[214:217], v141 offset:3072
	ds_read_b128 v[218:221], v141 offset:4096
	ds_read_b128 v[222:225], v141 offset:5120
	ds_read_b128 v[226:229], v141 offset:6144
	ds_read_b128 v[230:233], v141 offset:7168
	s_setprio 0
	s_cmp_eq_u64 s[52:53], 0
	s_cbranch_scc0 .Lpr_604
	s_setprio 1

.LBB0_604:
	s_add_i32 s22, 0, 0x10000
	s_add_i32 s23, 0, 0x14000
	v_add_u32_e32 v150, s22, v139
	v_add_u32_e32 v162, s23, v139
	ds_read_b128 v[134:137], v150
	ds_read_b128 v[142:145], v150 offset:1024
	ds_read_b128 v[146:149], v150 offset:2048
	ds_read_b128 v[150:153], v150 offset:3072
	ds_read_b128 v[154:157], v162
	ds_read_b128 v[158:161], v162 offset:1024
	ds_read_b128 v[182:185], v162 offset:2048
	ds_read_b128 v[186:189], v162 offset:3072
	ds_read_b128 v[190:193], v141
	ds_read_b128 v[194:197], v141 offset:1024
	ds_read_b128 v[198:201], v141 offset:2048
	ds_read_b128 v[214:217], v141 offset:3072
	ds_read_b128 v[218:221], v141 offset:4096
	ds_read_b128 v[222:225], v141 offset:5120
	ds_read_b128 v[226:229], v141 offset:6144
	ds_read_b128 v[230:233], v141 offset:7168
	s_add_u32 s20, s6, 0xfffe0080
	s_addc_u32 s21, s7, -1
	s_cmp_eq_u32 s84, 4
	s_cselect_b32 s69, s42, s21
	s_cselect_b32 s68, s43, s20
	s_cselect_b32 s21, s46, s51
	s_cselect_b32 s20, s47, s49
	s_add_i32 m0, s89, 0xc000
	v_lshl_add_u64 v[162:163], s[6:7], 0, v[132:133]
	global_load_lds_dwordx4 v[162:163], off
	v_lshl_add_u64 v[162:163], v[162:163], 0, s[64:65]
	s_add_i32 m0, s89, 0xe000
	s_nop 0
	global_load_lds_dwordx4 v[162:163], off
	s_waitcnt vmcnt(8)
	s_waitcnt lgkmcnt(0)
	s_barrier
	s_waitcnt lgkmcnt(0)
	v_mfma_f32_16x16x32_bf16 v[126:129], v[134:137], v[190:193], v[126:129]
	v_mfma_f32_16x16x32_bf16 v[126:129], v[142:145], v[194:197], v[126:129]
	v_mfma_f32_16x16x32_bf16 v[122:125], v[146:149], v[190:193], v[122:125]
	v_mfma_f32_16x16x32_bf16 v[122:125], v[150:153], v[194:197], v[122:125]
	v_mfma_f32_16x16x32_bf16 v[110:113], v[134:137], v[198:201], v[110:113]
	v_mfma_f32_16x16x32_bf16 v[110:113], v[142:145], v[214:217], v[110:113]
	v_mfma_f32_16x16x32_bf16 v[106:109], v[146:149], v[198:201], v[106:109]
	v_mfma_f32_16x16x32_bf16 v[106:109], v[150:153], v[214:217], v[106:109]
	v_mfma_f32_16x16x32_bf16 v[94:97], v[134:137], v[218:221], v[94:97]
	v_mfma_f32_16x16x32_bf16 v[94:97], v[142:145], v[222:225], v[94:97]
	v_mfma_f32_16x16x32_bf16 v[90:93], v[146:149], v[218:221], v[90:93]
	v_mfma_f32_16x16x32_bf16 v[90:93], v[150:153], v[222:225], v[90:93]
	v_mfma_f32_16x16x32_bf16 v[78:81], v[134:137], v[226:229], v[78:81]
	v_mfma_f32_16x16x32_bf16 v[78:81], v[142:145], v[230:233], v[78:81]
	v_mfma_f32_16x16x32_bf16 v[74:77], v[146:149], v[226:229], v[74:77]
	v_mfma_f32_16x16x32_bf16 v[74:77], v[150:153], v[230:233], v[74:77]
	v_mfma_f32_16x16x32_bf16 v[118:121], v[154:157], v[190:193], v[118:121]
	v_mfma_f32_16x16x32_bf16 v[118:121], v[158:161], v[194:197], v[118:121]
	v_mfma_f32_16x16x32_bf16 v[114:117], v[182:185], v[190:193], v[114:117]
	v_mfma_f32_16x16x32_bf16 v[114:117], v[186:189], v[194:197], v[114:117]
	v_mfma_f32_16x16x32_bf16 v[102:105], v[154:157], v[198:201], v[102:105]
	v_mfma_f32_16x16x32_bf16 v[102:105], v[158:161], v[214:217], v[102:105]
	v_mfma_f32_16x16x32_bf16 v[98:101], v[182:185], v[198:201], v[98:101]
	v_mfma_f32_16x16x32_bf16 v[98:101], v[186:189], v[214:217], v[98:101]
	v_mfma_f32_16x16x32_bf16 v[86:89], v[154:157], v[218:221], v[86:89]
	v_mfma_f32_16x16x32_bf16 v[86:89], v[158:161], v[222:225], v[86:89]
	v_mfma_f32_16x16x32_bf16 v[82:85], v[182:185], v[218:221], v[82:85]
	v_mfma_f32_16x16x32_bf16 v[82:85], v[186:189], v[222:225], v[82:85]
	v_mfma_f32_16x16x32_bf16 v[70:73], v[154:157], v[226:229], v[70:73]
	v_mfma_f32_16x16x32_bf16 v[70:73], v[158:161], v[230:233], v[70:73]
	v_mfma_f32_16x16x32_bf16 v[66:69], v[182:185], v[226:229], v[66:69]
	v_mfma_f32_16x16x32_bf16 v[66:69], v[186:189], v[230:233], v[66:69]
	s_barrier
	ds_read_b128 v[190:193], v141 offset:16384
	ds_read_b128 v[194:197], v141 offset:17408
	ds_read_b128 v[198:201], v141 offset:18432
	ds_read_b128 v[214:217], v141 offset:19456
	ds_read_b128 v[218:221], v141 offset:20480
	ds_read_b128 v[222:225], v141 offset:21504
	ds_read_b128 v[226:229], v141 offset:22528
	ds_read_b128 v[230:233], v141 offset:23552
	v_lshl_add_u64 v[162:163], s[20:21], 0, v[0:1]
	s_add_i32 s20, s22, s88
	s_mov_b32 m0, s20
	s_nop 0
	s_nop 0
	global_load_lds_dwordx4 v[162:163], off
	v_lshl_add_u64 v[202:203], v[162:163], 0, s[64:65]
	s_add_i32 m0, s20, 0x2000
	s_add_i32 s20, s23, s88
	global_load_lds_dwordx4 v[202:203], off
	v_lshl_add_u64 v[202:203], v[162:163], 0, s[72:73]
	s_mov_b32 m0, s20
	s_nop 0
	global_load_lds_dwordx4 v[202:203], off
	v_lshl_add_u64 v[202:203], v[162:163], 0, s[74:75]
	s_add_i32 m0, s20, 0x2000
	s_nop 0
	global_load_lds_dwordx4 v[202:203], off
	v_lshl_add_u64 v[202:203], s[68:69], 0, v[130:131]
	s_mov_b32 m0, s89
	v_lshl_add_u64 v[234:235], v[202:203], 0, s[64:65]
	global_load_lds_dwordx4 v[202:203], off
	s_mov_b32 m0, s90
	s_nop 0
	global_load_lds_dwordx4 v[234:235], off
	s_waitcnt vmcnt(8)
	s_waitcnt lgkmcnt(0)
	s_barrier
	s_waitcnt lgkmcnt(0)
	v_mfma_f32_16x16x32_bf16 v[62:65], v[134:137], v[190:193], v[62:65]
	v_mfma_f32_16x16x32_bf16 v[62:65], v[142:145], v[194:197], v[62:65]
	v_mfma_f32_16x16x32_bf16 v[58:61], v[146:149], v[190:193], v[58:61]
	v_mfma_f32_16x16x32_bf16 v[58:61], v[150:153], v[194:197], v[58:61]
	v_mfma_f32_16x16x32_bf16 v[46:49], v[134:137], v[198:201], v[46:49]
	v_mfma_f32_16x16x32_bf16 v[46:49], v[142:145], v[214:217], v[46:49]
	v_mfma_f32_16x16x32_bf16 v[42:45], v[146:149], v[198:201], v[42:45]
	v_mfma_f32_16x16x32_bf16 v[42:45], v[150:153], v[214:217], v[42:45]
	v_mfma_f32_16x16x32_bf16 v[30:33], v[134:137], v[218:221], v[30:33]
	v_mfma_f32_16x16x32_bf16 v[30:33], v[142:145], v[222:225], v[30:33]
	v_mfma_f32_16x16x32_bf16 v[26:29], v[146:149], v[218:221], v[26:29]
	v_mfma_f32_16x16x32_bf16 v[26:29], v[150:153], v[222:225], v[26:29]
	v_mfma_f32_16x16x32_bf16 v[14:17], v[134:137], v[226:229], v[14:17]
	v_mfma_f32_16x16x32_bf16 v[14:17], v[142:145], v[230:233], v[14:17]
	v_mfma_f32_16x16x32_bf16 v[10:13], v[146:149], v[226:229], v[10:13]
	v_mfma_f32_16x16x32_bf16 v[10:13], v[150:153], v[230:233], v[10:13]
	v_mfma_f32_16x16x32_bf16 v[54:57], v[154:157], v[190:193], v[54:57]
	v_mfma_f32_16x16x32_bf16 v[54:57], v[158:161], v[194:197], v[54:57]
	v_mfma_f32_16x16x32_bf16 v[50:53], v[182:185], v[190:193], v[50:53]
	v_mfma_f32_16x16x32_bf16 v[50:53], v[186:189], v[194:197], v[50:53]
	v_mfma_f32_16x16x32_bf16 v[38:41], v[154:157], v[198:201], v[38:41]
	v_mfma_f32_16x16x32_bf16 v[38:41], v[158:161], v[214:217], v[38:41]
	v_mfma_f32_16x16x32_bf16 v[34:37], v[182:185], v[198:201], v[34:37]
	v_mfma_f32_16x16x32_bf16 v[34:37], v[186:189], v[214:217], v[34:37]
	v_mfma_f32_16x16x32_bf16 v[22:25], v[154:157], v[218:221], v[22:25]
	v_mfma_f32_16x16x32_bf16 v[22:25], v[158:161], v[222:225], v[22:25]
	v_mfma_f32_16x16x32_bf16 v[18:21], v[182:185], v[218:221], v[18:21]
	v_mfma_f32_16x16x32_bf16 v[18:21], v[186:189], v[222:225], v[18:21]
	v_mfma_f32_16x16x32_bf16 v[6:9], v[154:157], v[226:229], v[6:9]
	v_mfma_f32_16x16x32_bf16 v[6:9], v[158:161], v[230:233], v[6:9]
	v_mfma_f32_16x16x32_bf16 v[2:5], v[182:185], v[226:229], v[2:5]
	v_mfma_f32_16x16x32_bf16 v[2:5], v[186:189], v[230:233], v[2:5]
	s_barrier
	s_add_i32 s20, 0, 0x18000
	s_add_i32 s21, 0, 0x1c000
	v_add_u32_e32 v150, s20, v139
	v_add_u32_e32 v186, s21, v139
	ds_read_b128 v[134:137], v150
	ds_read_b128 v[142:145], v150 offset:1024
	ds_read_b128 v[146:149], v150 offset:2048
	ds_read_b128 v[150:153], v150 offset:3072
	ds_read_b128 v[154:157], v186
	ds_read_b128 v[158:161], v186 offset:1024
	ds_read_b128 v[182:185], v186 offset:2048
	ds_read_b128 v[186:189], v186 offset:3072
	ds_read_b128 v[190:193], v141 offset:32768
	ds_read_b128 v[194:197], v141 offset:33792
	ds_read_b128 v[198:201], v141 offset:34816
	ds_read_b128 v[214:217], v141 offset:35840
	ds_read_b128 v[218:221], v141 offset:36864
	ds_read_b128 v[222:225], v141 offset:37888
	ds_read_b128 v[226:229], v141 offset:38912
	ds_read_b128 v[230:233], v141 offset:39936
	s_mov_b32 m0, s91
	v_lshl_add_u64 v[234:235], v[202:203], 0, s[72:73]
	global_load_lds_dwordx4 v[234:235], off
	v_lshl_add_u64 v[234:235], v[202:203], 0, s[74:75]
	s_mov_b32 m0, s96
	s_nop 0
	global_load_lds_dwordx4 v[234:235], off
	s_waitcnt vmcnt(8)
	s_waitcnt lgkmcnt(0)
	s_barrier
	s_waitcnt lgkmcnt(0)
	v_mfma_f32_16x16x32_bf16 v[126:129], v[134:137], v[190:193], v[126:129]
	v_mfma_f32_16x16x32_bf16 v[126:129], v[142:145], v[194:197], v[126:129]
	v_mfma_f32_16x16x32_bf16 v[122:125], v[146:149], v[190:193], v[122:125]
	v_mfma_f32_16x16x32_bf16 v[122:125], v[150:153], v[194:197], v[122:125]
	v_mfma_f32_16x16x32_bf16 v[110:113], v[134:137], v[198:201], v[110:113]
	v_mfma_f32_16x16x32_bf16 v[110:113], v[142:145], v[214:217], v[110:113]
	v_mfma_f32_16x16x32_bf16 v[106:109], v[146:149], v[198:201], v[106:109]
	v_mfma_f32_16x16x32_bf16 v[106:109], v[150:153], v[214:217], v[106:109]
	v_mfma_f32_16x16x32_bf16 v[94:97], v[134:137], v[218:221], v[94:97]
	v_mfma_f32_16x16x32_bf16 v[94:97], v[142:145], v[222:225], v[94:97]
	v_mfma_f32_16x16x32_bf16 v[90:93], v[146:149], v[218:221], v[90:93]
	v_mfma_f32_16x16x32_bf16 v[90:93], v[150:153], v[222:225], v[90:93]
	v_mfma_f32_16x16x32_bf16 v[78:81], v[134:137], v[226:229], v[78:81]
	v_mfma_f32_16x16x32_bf16 v[78:81], v[142:145], v[230:233], v[78:81]
	v_mfma_f32_16x16x32_bf16 v[74:77], v[146:149], v[226:229], v[74:77]
	v_mfma_f32_16x16x32_bf16 v[74:77], v[150:153], v[230:233], v[74:77]
	v_mfma_f32_16x16x32_bf16 v[118:121], v[154:157], v[190:193], v[118:121]
	v_mfma_f32_16x16x32_bf16 v[118:121], v[158:161], v[194:197], v[118:121]
	v_mfma_f32_16x16x32_bf16 v[114:117], v[182:185], v[190:193], v[114:117]
	v_mfma_f32_16x16x32_bf16 v[114:117], v[186:189], v[194:197], v[114:117]
	v_mfma_f32_16x16x32_bf16 v[102:105], v[154:157], v[198:201], v[102:105]
	v_mfma_f32_16x16x32_bf16 v[102:105], v[158:161], v[214:217], v[102:105]
	v_mfma_f32_16x16x32_bf16 v[98:101], v[182:185], v[198:201], v[98:101]
	v_mfma_f32_16x16x32_bf16 v[98:101], v[186:189], v[214:217], v[98:101]
	v_mfma_f32_16x16x32_bf16 v[86:89], v[154:157], v[218:221], v[86:89]
	v_mfma_f32_16x16x32_bf16 v[86:89], v[158:161], v[222:225], v[86:89]
	v_mfma_f32_16x16x32_bf16 v[82:85], v[182:185], v[218:221], v[82:85]
	v_mfma_f32_16x16x32_bf16 v[82:85], v[186:189], v[222:225], v[82:85]
	v_mfma_f32_16x16x32_bf16 v[70:73], v[154:157], v[226:229], v[70:73]
	v_mfma_f32_16x16x32_bf16 v[70:73], v[158:161], v[230:233], v[70:73]
	v_mfma_f32_16x16x32_bf16 v[66:69], v[182:185], v[226:229], v[66:69]
	v_mfma_f32_16x16x32_bf16 v[66:69], v[186:189], v[230:233], v[66:69]
	s_barrier
	ds_read_b128 v[190:193], v141 offset:49152
	ds_read_b128 v[194:197], v141 offset:50176
	ds_read_b128 v[198:201], v141 offset:51200
	ds_read_b128 v[214:217], v141 offset:52224
	ds_read_b128 v[218:221], v141 offset:53248
	ds_read_b128 v[222:225], v141 offset:54272
	ds_read_b128 v[226:229], v141 offset:55296
	ds_read_b128 v[230:233], v141 offset:56320
	s_add_i32 s20, s20, s88
	s_mov_b32 m0, s20
	v_lshl_add_u64 v[234:235], v[162:163], 0, s[34:35]
	global_load_lds_dwordx4 v[234:235], off
	v_lshl_add_u64 v[234:235], v[162:163], 0, s[80:81]
	s_add_i32 m0, s20, 0x2000
	s_add_i32 s20, s21, s88
	global_load_lds_dwordx4 v[234:235], off
	v_lshl_add_u64 v[234:235], v[162:163], 0, s[38:39]
	s_mov_b32 m0, s20
	v_lshl_add_u64 v[162:163], v[162:163], 0, s[86:87]
	global_load_lds_dwordx4 v[234:235], off
	s_add_i32 m0, s20, 0x2000
	s_nop 0
	global_load_lds_dwordx4 v[162:163], off
	v_lshl_add_u64 v[162:163], v[202:203], 0, s[34:35]
	s_mov_b32 m0, s97
	s_nop 0
	global_load_lds_dwordx4 v[162:163], off
	v_lshl_add_u64 v[162:163], v[202:203], 0, s[80:81]
	s_mov_b32 m0, s58
	s_nop 0
	global_load_lds_dwordx4 v[162:163], off
	s_waitcnt vmcnt(8)
	s_waitcnt lgkmcnt(0)
	s_barrier
	s_waitcnt lgkmcnt(0)
	v_mfma_f32_16x16x32_bf16 v[62:65], v[134:137], v[190:193], v[62:65]
	v_mfma_f32_16x16x32_bf16 v[62:65], v[142:145], v[194:197], v[62:65]
	v_mfma_f32_16x16x32_bf16 v[58:61], v[146:149], v[190:193], v[58:61]
	v_mfma_f32_16x16x32_bf16 v[58:61], v[150:153], v[194:197], v[58:61]
	v_mfma_f32_16x16x32_bf16 v[46:49], v[134:137], v[198:201], v[46:49]
	v_mfma_f32_16x16x32_bf16 v[46:49], v[142:145], v[214:217], v[46:49]
	v_mfma_f32_16x16x32_bf16 v[42:45], v[146:149], v[198:201], v[42:45]
	v_mfma_f32_16x16x32_bf16 v[42:45], v[150:153], v[214:217], v[42:45]
	v_mfma_f32_16x16x32_bf16 v[30:33], v[134:137], v[218:221], v[30:33]
	v_mfma_f32_16x16x32_bf16 v[30:33], v[142:145], v[222:225], v[30:33]
	v_mfma_f32_16x16x32_bf16 v[26:29], v[146:149], v[218:221], v[26:29]
	v_mfma_f32_16x16x32_bf16 v[26:29], v[150:153], v[222:225], v[26:29]
	v_mfma_f32_16x16x32_bf16 v[14:17], v[134:137], v[226:229], v[14:17]
	v_mfma_f32_16x16x32_bf16 v[14:17], v[142:145], v[230:233], v[14:17]
	v_mfma_f32_16x16x32_bf16 v[10:13], v[146:149], v[226:229], v[10:13]
	v_mfma_f32_16x16x32_bf16 v[10:13], v[150:153], v[230:233], v[10:13]
	s_add_i32 s84, s84, 2
	s_add_u32 s6, s6, 0x100
	s_addc_u32 s7, s7, 0
	s_add_u32 s49, s49, 0x100
	s_addc_u32 s51, s51, 0
	v_mfma_f32_16x16x32_bf16 v[54:57], v[154:157], v[190:193], v[54:57]
	v_mfma_f32_16x16x32_bf16 v[54:57], v[158:161], v[194:197], v[54:57]
	v_mfma_f32_16x16x32_bf16 v[50:53], v[182:185], v[190:193], v[50:53]
	v_mfma_f32_16x16x32_bf16 v[50:53], v[186:189], v[194:197], v[50:53]
	v_mfma_f32_16x16x32_bf16 v[38:41], v[154:157], v[198:201], v[38:41]
	v_mfma_f32_16x16x32_bf16 v[38:41], v[158:161], v[214:217], v[38:41]
	v_mfma_f32_16x16x32_bf16 v[34:37], v[182:185], v[198:201], v[34:37]
	v_mfma_f32_16x16x32_bf16 v[34:37], v[186:189], v[214:217], v[34:37]
	v_mfma_f32_16x16x32_bf16 v[22:25], v[154:157], v[218:221], v[22:25]
	v_mfma_f32_16x16x32_bf16 v[22:25], v[158:161], v[222:225], v[22:25]
	v_mfma_f32_16x16x32_bf16 v[18:21], v[182:185], v[218:221], v[18:21]
	v_mfma_f32_16x16x32_bf16 v[18:21], v[186:189], v[222:225], v[18:21]
	v_mfma_f32_16x16x32_bf16 v[6:9], v[154:157], v[226:229], v[6:9]
	v_mfma_f32_16x16x32_bf16 v[6:9], v[158:161], v[230:233], v[6:9]
	v_mfma_f32_16x16x32_bf16 v[2:5], v[182:185], v[226:229], v[2:5]
	v_mfma_f32_16x16x32_bf16 v[2:5], v[186:189], v[230:233], v[2:5]
	s_barrier
	s_cmp_gt_u32 s84, 5
	s_cbranch_scc0 .LBB0_604
	s_setprio 0
	s_cmp_eq_u64 s[52:53], 0
	s_cbranch_scc1 .Lpx_604
	s_setprio 1
.Lpx_604:
	s_and_b64 vcc, exec, s[52:53]
	s_cbranch_vccz .LBB0_607
	s_barrier

.LBB0_777:
	s_ashr_i32 s61, s60, 31
	s_lshl_b64 s[20:21], s[60:61], 19
	s_add_u32 s62, s94, s20
	s_addc_u32 s63, s95, s21
	s_and_b64 s[20:21], s[56:57], exec
	s_cselect_b32 s61, s63, s77
	s_cselect_b32 s85, s62, s76
	s_ashr_i32 s59, s58, 31
	s_lshl_b64 s[20:21], s[58:59], 19
	s_add_u32 s68, s15, s20
	s_addc_u32 s69, s42, s21
	s_and_b64 s[20:21], s[56:57], exec
	s_cselect_b32 s59, s69, s79
	s_cselect_b32 s86, s68, s78
	s_add_u32 s76, s76, 0x40080
	s_addc_u32 s77, s77, 0
	s_add_u32 s87, s78, 0x100
	v_mov_b32_e32 v2, 0
	s_addc_u32 vcc_lo, s79, 0
	s_mov_b32 vcc_hi, -2
	s_waitcnt lgkmcnt(0)
	s_add_i32 s22, 0, 0x10000
	s_add_i32 s23, 0, 0x14000
	v_add_u32_e32 v142, s22, v193
	v_add_u32_e32 v158, s23, v193
	ds_read_b128 v[130:133], v142
	ds_read_b128 v[134:137], v142 offset:1024
	ds_read_b128 v[138:141], v142 offset:2048
	ds_read_b128 v[142:145], v142 offset:3072
	ds_read_b128 v[146:149], v158
	ds_read_b128 v[150:153], v158 offset:1024
	ds_read_b128 v[154:157], v158 offset:2048
	ds_read_b128 v[158:161], v158 offset:3072
	ds_read_b128 v[184:187], v196
	ds_read_b128 v[188:191], v196 offset:1024
	ds_read_b128 v[198:201], v196 offset:2048
	ds_read_b128 v[214:217], v196 offset:3072
	ds_read_b128 v[218:221], v196 offset:4096
	ds_read_b128 v[222:225], v196 offset:5120
	ds_read_b128 v[226:229], v196 offset:6144
	ds_read_b128 v[230:233], v196 offset:7168
	s_setprio 0
	s_cmp_eq_u64 s[50:51], 0
	s_cbranch_scc0 .Lpr_778
	s_setprio 1

.LBB0_778:
	s_add_i32 s22, 0, 0x10000
	s_add_i32 s23, 0, 0x14000
	v_add_u32_e32 v142, s22, v193
	v_add_u32_e32 v158, s23, v193
	ds_read_b128 v[130:133], v142
	ds_read_b128 v[134:137], v142 offset:1024
	ds_read_b128 v[138:141], v142 offset:2048
	ds_read_b128 v[142:145], v142 offset:3072
	ds_read_b128 v[146:149], v158
	ds_read_b128 v[150:153], v158 offset:1024
	ds_read_b128 v[154:157], v158 offset:2048
	ds_read_b128 v[158:161], v158 offset:3072
	ds_read_b128 v[184:187], v196
	ds_read_b128 v[188:191], v196 offset:1024
	ds_read_b128 v[198:201], v196 offset:2048
	ds_read_b128 v[214:217], v196 offset:3072
	ds_read_b128 v[218:221], v196 offset:4096
	ds_read_b128 v[222:225], v196 offset:5120
	ds_read_b128 v[226:229], v196 offset:6144
	ds_read_b128 v[230:233], v196 offset:7168
	s_add_u32 s20, s76, 0xfffc0080
	s_addc_u32 s21, s77, -1
	s_cmp_eq_u32 vcc_hi, 12
	s_cselect_b32 s79, s61, s21
	s_cselect_b32 s78, s85, s20
	s_cselect_b32 s21, s59, vcc_lo
	s_cselect_b32 s20, s86, s87
	s_add_i32 m0, s43, 0xc000
	v_lshl_add_u64 v[202:203], s[76:77], 0, v[182:183]
	global_load_lds_dwordx4 v[202:203], off
	v_lshl_add_u64 v[202:203], v[202:203], 0, s[72:73]
	s_add_i32 m0, s43, 0xe000
	s_nop 0
	global_load_lds_dwordx4 v[202:203], off
	s_waitcnt vmcnt(8)
	s_waitcnt lgkmcnt(0)
	s_barrier
	s_waitcnt lgkmcnt(0)
	v_mfma_f32_16x16x32_bf16 v[126:129], v[130:133], v[184:187], v[126:129]
	v_mfma_f32_16x16x32_bf16 v[126:129], v[134:137], v[188:191], v[126:129]
	v_mfma_f32_16x16x32_bf16 v[122:125], v[138:141], v[184:187], v[122:125]
	v_mfma_f32_16x16x32_bf16 v[122:125], v[142:145], v[188:191], v[122:125]
	v_mfma_f32_16x16x32_bf16 v[110:113], v[130:133], v[198:201], v[110:113]
	v_mfma_f32_16x16x32_bf16 v[110:113], v[134:137], v[214:217], v[110:113]
	v_mfma_f32_16x16x32_bf16 v[106:109], v[138:141], v[198:201], v[106:109]
	v_mfma_f32_16x16x32_bf16 v[106:109], v[142:145], v[214:217], v[106:109]
	v_mfma_f32_16x16x32_bf16 v[94:97], v[130:133], v[218:221], v[94:97]
	v_mfma_f32_16x16x32_bf16 v[94:97], v[134:137], v[222:225], v[94:97]
	v_mfma_f32_16x16x32_bf16 v[90:93], v[138:141], v[218:221], v[90:93]
	v_mfma_f32_16x16x32_bf16 v[90:93], v[142:145], v[222:225], v[90:93]
	v_mfma_f32_16x16x32_bf16 v[78:81], v[130:133], v[226:229], v[78:81]
	v_mfma_f32_16x16x32_bf16 v[78:81], v[134:137], v[230:233], v[78:81]
	v_mfma_f32_16x16x32_bf16 v[74:77], v[138:141], v[226:229], v[74:77]
	v_mfma_f32_16x16x32_bf16 v[74:77], v[142:145], v[230:233], v[74:77]
	v_mfma_f32_16x16x32_bf16 v[118:121], v[146:149], v[184:187], v[118:121]
	v_mfma_f32_16x16x32_bf16 v[118:121], v[150:153], v[188:191], v[118:121]
	v_mfma_f32_16x16x32_bf16 v[114:117], v[154:157], v[184:187], v[114:117]
	v_mfma_f32_16x16x32_bf16 v[114:117], v[158:161], v[188:191], v[114:117]
	v_mfma_f32_16x16x32_bf16 v[102:105], v[146:149], v[198:201], v[102:105]
	v_mfma_f32_16x16x32_bf16 v[102:105], v[150:153], v[214:217], v[102:105]
	v_mfma_f32_16x16x32_bf16 v[98:101], v[154:157], v[198:201], v[98:101]
	v_mfma_f32_16x16x32_bf16 v[98:101], v[158:161], v[214:217], v[98:101]
	v_mfma_f32_16x16x32_bf16 v[86:89], v[146:149], v[218:221], v[86:89]
	v_mfma_f32_16x16x32_bf16 v[86:89], v[150:153], v[222:225], v[86:89]
	v_mfma_f32_16x16x32_bf16 v[82:85], v[154:157], v[218:221], v[82:85]
	v_mfma_f32_16x16x32_bf16 v[82:85], v[158:161], v[222:225], v[82:85]
	v_mfma_f32_16x16x32_bf16 v[70:73], v[146:149], v[226:229], v[70:73]
	v_mfma_f32_16x16x32_bf16 v[70:73], v[150:153], v[230:233], v[70:73]
	v_mfma_f32_16x16x32_bf16 v[66:69], v[154:157], v[226:229], v[66:69]
	v_mfma_f32_16x16x32_bf16 v[66:69], v[158:161], v[230:233], v[66:69]
	s_barrier
	ds_read_b128 v[184:187], v196 offset:16384
	ds_read_b128 v[188:191], v196 offset:17408
	ds_read_b128 v[198:201], v196 offset:18432
	ds_read_b128 v[214:217], v196 offset:19456
	ds_read_b128 v[218:221], v196 offset:20480
	ds_read_b128 v[222:225], v196 offset:21504
	ds_read_b128 v[226:229], v196 offset:22528
	ds_read_b128 v[230:233], v196 offset:23552
	v_lshl_add_u64 v[202:203], s[20:21], 0, v[0:1]
	s_add_i32 s20, s22, s14
	s_mov_b32 m0, s20
	s_nop 0
	s_nop 0
	global_load_lds_dwordx4 v[202:203], off
	v_lshl_add_u64 v[234:235], v[202:203], 0, s[72:73]
	s_add_i32 m0, s20, 0x2000
	s_add_i32 s20, s23, s14
	global_load_lds_dwordx4 v[234:235], off
	v_lshl_add_u64 v[234:235], v[202:203], 0, s[28:29]
	s_mov_b32 m0, s20
	s_nop 0
	global_load_lds_dwordx4 v[234:235], off
	v_lshl_add_u64 v[234:235], v[202:203], 0, s[82:83]
	s_add_i32 m0, s20, 0x2000
	s_nop 0
	global_load_lds_dwordx4 v[234:235], off
	v_lshl_add_u64 v[234:235], s[78:79], 0, v[162:163]
	s_mov_b32 m0, s43
	v_lshl_add_u64 v[236:237], v[234:235], 0, s[72:73]
	global_load_lds_dwordx4 v[234:235], off
	s_mov_b32 m0, s46
	s_nop 0
	global_load_lds_dwordx4 v[236:237], off
	s_waitcnt vmcnt(8)
	s_waitcnt lgkmcnt(0)
	s_barrier
	s_waitcnt lgkmcnt(0)
	v_mfma_f32_16x16x32_bf16 v[62:65], v[130:133], v[184:187], v[62:65]
	v_mfma_f32_16x16x32_bf16 v[62:65], v[134:137], v[188:191], v[62:65]
	v_mfma_f32_16x16x32_bf16 v[58:61], v[138:141], v[184:187], v[58:61]
	v_mfma_f32_16x16x32_bf16 v[58:61], v[142:145], v[188:191], v[58:61]
	v_mfma_f32_16x16x32_bf16 v[46:49], v[130:133], v[198:201], v[46:49]
	v_mfma_f32_16x16x32_bf16 v[46:49], v[134:137], v[214:217], v[46:49]
	v_mfma_f32_16x16x32_bf16 v[42:45], v[138:141], v[198:201], v[42:45]
	v_mfma_f32_16x16x32_bf16 v[42:45], v[142:145], v[214:217], v[42:45]
	v_mfma_f32_16x16x32_bf16 v[30:33], v[130:133], v[218:221], v[30:33]
	v_mfma_f32_16x16x32_bf16 v[30:33], v[134:137], v[222:225], v[30:33]
	v_mfma_f32_16x16x32_bf16 v[26:29], v[138:141], v[218:221], v[26:29]
	v_mfma_f32_16x16x32_bf16 v[26:29], v[142:145], v[222:225], v[26:29]
	v_mfma_f32_16x16x32_bf16 v[14:17], v[130:133], v[226:229], v[14:17]
	v_mfma_f32_16x16x32_bf16 v[14:17], v[134:137], v[230:233], v[14:17]
	v_mfma_f32_16x16x32_bf16 v[10:13], v[138:141], v[226:229], v[10:13]
	v_mfma_f32_16x16x32_bf16 v[10:13], v[142:145], v[230:233], v[10:13]
	v_mfma_f32_16x16x32_bf16 v[54:57], v[146:149], v[184:187], v[54:57]
	v_mfma_f32_16x16x32_bf16 v[54:57], v[150:153], v[188:191], v[54:57]
	v_mfma_f32_16x16x32_bf16 v[50:53], v[154:157], v[184:187], v[50:53]
	v_mfma_f32_16x16x32_bf16 v[50:53], v[158:161], v[188:191], v[50:53]
	v_mfma_f32_16x16x32_bf16 v[38:41], v[146:149], v[198:201], v[38:41]
	v_mfma_f32_16x16x32_bf16 v[38:41], v[150:153], v[214:217], v[38:41]
	v_mfma_f32_16x16x32_bf16 v[34:37], v[154:157], v[198:201], v[34:37]
	v_mfma_f32_16x16x32_bf16 v[34:37], v[158:161], v[214:217], v[34:37]
	v_mfma_f32_16x16x32_bf16 v[22:25], v[146:149], v[218:221], v[22:25]
	v_mfma_f32_16x16x32_bf16 v[22:25], v[150:153], v[222:225], v[22:25]
	v_mfma_f32_16x16x32_bf16 v[18:21], v[154:157], v[218:221], v[18:21]
	v_mfma_f32_16x16x32_bf16 v[18:21], v[158:161], v[222:225], v[18:21]
	v_mfma_f32_16x16x32_bf16 v[6:9], v[146:149], v[226:229], v[6:9]
	v_mfma_f32_16x16x32_bf16 v[6:9], v[150:153], v[230:233], v[6:9]
	v_mfma_f32_16x16x32_bf16 v[2:5], v[154:157], v[226:229], v[2:5]
	v_mfma_f32_16x16x32_bf16 v[2:5], v[158:161], v[230:233], v[2:5]
	s_barrier
	s_add_i32 s20, 0, 0x18000
	s_add_i32 s21, 0, 0x1c000
	v_add_u32_e32 v142, s20, v193
	v_add_u32_e32 v158, s21, v193
	ds_read_b128 v[130:133], v142
	ds_read_b128 v[134:137], v142 offset:1024
	ds_read_b128 v[138:141], v142 offset:2048
	ds_read_b128 v[142:145], v142 offset:3072
	ds_read_b128 v[146:149], v158
	ds_read_b128 v[150:153], v158 offset:1024
	ds_read_b128 v[154:157], v158 offset:2048
	ds_read_b128 v[158:161], v158 offset:3072
	ds_read_b128 v[184:187], v196 offset:32768
	ds_read_b128 v[188:191], v196 offset:33792
	ds_read_b128 v[198:201], v196 offset:34816
	ds_read_b128 v[214:217], v196 offset:35840
	ds_read_b128 v[218:221], v196 offset:36864
	ds_read_b128 v[222:225], v196 offset:37888
	ds_read_b128 v[226:229], v196 offset:38912
	ds_read_b128 v[230:233], v196 offset:39936
	s_mov_b32 m0, s47
	v_lshl_add_u64 v[236:237], v[234:235], 0, s[28:29]
	global_load_lds_dwordx4 v[236:237], off
	v_lshl_add_u64 v[236:237], v[234:235], 0, s[82:83]
	s_mov_b32 m0, s88
	s_nop 0
	global_load_lds_dwordx4 v[236:237], off
	s_waitcnt vmcnt(8)
	s_waitcnt lgkmcnt(0)
	s_barrier
	s_waitcnt lgkmcnt(0)
	v_mfma_f32_16x16x32_bf16 v[126:129], v[130:133], v[184:187], v[126:129]
	v_mfma_f32_16x16x32_bf16 v[126:129], v[134:137], v[188:191], v[126:129]
	v_mfma_f32_16x16x32_bf16 v[122:125], v[138:141], v[184:187], v[122:125]
	v_mfma_f32_16x16x32_bf16 v[122:125], v[142:145], v[188:191], v[122:125]
	v_mfma_f32_16x16x32_bf16 v[110:113], v[130:133], v[198:201], v[110:113]
	v_mfma_f32_16x16x32_bf16 v[110:113], v[134:137], v[214:217], v[110:113]
	v_mfma_f32_16x16x32_bf16 v[106:109], v[138:141], v[198:201], v[106:109]
	v_mfma_f32_16x16x32_bf16 v[106:109], v[142:145], v[214:217], v[106:109]
	v_mfma_f32_16x16x32_bf16 v[94:97], v[130:133], v[218:221], v[94:97]
	v_mfma_f32_16x16x32_bf16 v[94:97], v[134:137], v[222:225], v[94:97]
	v_mfma_f32_16x16x32_bf16 v[90:93], v[138:141], v[218:221], v[90:93]
	v_mfma_f32_16x16x32_bf16 v[90:93], v[142:145], v[222:225], v[90:93]
	v_mfma_f32_16x16x32_bf16 v[78:81], v[130:133], v[226:229], v[78:81]
	v_mfma_f32_16x16x32_bf16 v[78:81], v[134:137], v[230:233], v[78:81]
	v_mfma_f32_16x16x32_bf16 v[74:77], v[138:141], v[226:229], v[74:77]
	v_mfma_f32_16x16x32_bf16 v[74:77], v[142:145], v[230:233], v[74:77]
	v_mfma_f32_16x16x32_bf16 v[118:121], v[146:149], v[184:187], v[118:121]
	v_mfma_f32_16x16x32_bf16 v[118:121], v[150:153], v[188:191], v[118:121]
	v_mfma_f32_16x16x32_bf16 v[114:117], v[154:157], v[184:187], v[114:117]
	v_mfma_f32_16x16x32_bf16 v[114:117], v[158:161], v[188:191], v[114:117]
	v_mfma_f32_16x16x32_bf16 v[102:105], v[146:149], v[198:201], v[102:105]
	v_mfma_f32_16x16x32_bf16 v[102:105], v[150:153], v[214:217], v[102:105]
	v_mfma_f32_16x16x32_bf16 v[98:101], v[154:157], v[198:201], v[98:101]
	v_mfma_f32_16x16x32_bf16 v[98:101], v[158:161], v[214:217], v[98:101]
	v_mfma_f32_16x16x32_bf16 v[86:89], v[146:149], v[218:221], v[86:89]
	v_mfma_f32_16x16x32_bf16 v[86:89], v[150:153], v[222:225], v[86:89]
	v_mfma_f32_16x16x32_bf16 v[82:85], v[154:157], v[218:221], v[82:85]
	v_mfma_f32_16x16x32_bf16 v[82:85], v[158:161], v[222:225], v[82:85]
	v_mfma_f32_16x16x32_bf16 v[70:73], v[146:149], v[226:229], v[70:73]
	v_mfma_f32_16x16x32_bf16 v[70:73], v[150:153], v[230:233], v[70:73]
	v_mfma_f32_16x16x32_bf16 v[66:69], v[154:157], v[226:229], v[66:69]
	v_mfma_f32_16x16x32_bf16 v[66:69], v[158:161], v[230:233], v[66:69]
	s_barrier
	ds_read_b128 v[184:187], v196 offset:49152
	ds_read_b128 v[188:191], v196 offset:50176
	ds_read_b128 v[198:201], v196 offset:51200
	ds_read_b128 v[214:217], v196 offset:52224
	ds_read_b128 v[218:221], v196 offset:53248
	ds_read_b128 v[222:225], v196 offset:54272
	ds_read_b128 v[226:229], v196 offset:55296
	ds_read_b128 v[230:233], v196 offset:56320
	s_add_i32 s20, s20, s14
	s_mov_b32 m0, s20
	v_lshl_add_u64 v[236:237], v[202:203], 0, s[34:35]
	global_load_lds_dwordx4 v[236:237], off
	v_lshl_add_u64 v[236:237], v[202:203], 0, s[38:39]
	s_add_i32 m0, s20, 0x2000
	s_add_i32 s20, s21, s14
	global_load_lds_dwordx4 v[236:237], off
	v_lshl_add_u64 v[236:237], v[202:203], 0, s[44:45]
	s_mov_b32 m0, s20
	v_lshl_add_u64 v[202:203], v[202:203], 0, s[10:11]
	global_load_lds_dwordx4 v[236:237], off
	s_add_i32 m0, s20, 0x2000
	s_nop 0
	global_load_lds_dwordx4 v[202:203], off
	v_lshl_add_u64 v[202:203], v[234:235], 0, s[34:35]
	s_mov_b32 m0, s89
	s_nop 0
	global_load_lds_dwordx4 v[202:203], off
	v_lshl_add_u64 v[202:203], v[234:235], 0, s[38:39]
	s_mov_b32 m0, s90
	s_nop 0
	global_load_lds_dwordx4 v[202:203], off
	s_waitcnt vmcnt(8)
	s_waitcnt lgkmcnt(0)
	s_barrier
	s_waitcnt lgkmcnt(0)
	v_mfma_f32_16x16x32_bf16 v[62:65], v[130:133], v[184:187], v[62:65]
	v_mfma_f32_16x16x32_bf16 v[62:65], v[134:137], v[188:191], v[62:65]
	v_mfma_f32_16x16x32_bf16 v[58:61], v[138:141], v[184:187], v[58:61]
	v_mfma_f32_16x16x32_bf16 v[58:61], v[142:145], v[188:191], v[58:61]
	v_mfma_f32_16x16x32_bf16 v[46:49], v[130:133], v[198:201], v[46:49]
	v_mfma_f32_16x16x32_bf16 v[46:49], v[134:137], v[214:217], v[46:49]
	v_mfma_f32_16x16x32_bf16 v[42:45], v[138:141], v[198:201], v[42:45]
	v_mfma_f32_16x16x32_bf16 v[42:45], v[142:145], v[214:217], v[42:45]
	v_mfma_f32_16x16x32_bf16 v[30:33], v[130:133], v[218:221], v[30:33]
	v_mfma_f32_16x16x32_bf16 v[30:33], v[134:137], v[222:225], v[30:33]
	v_mfma_f32_16x16x32_bf16 v[26:29], v[138:141], v[218:221], v[26:29]
	v_mfma_f32_16x16x32_bf16 v[26:29], v[142:145], v[222:225], v[26:29]
	v_mfma_f32_16x16x32_bf16 v[14:17], v[130:133], v[226:229], v[14:17]
	v_mfma_f32_16x16x32_bf16 v[14:17], v[134:137], v[230:233], v[14:17]
	v_mfma_f32_16x16x32_bf16 v[10:13], v[138:141], v[226:229], v[10:13]
	v_mfma_f32_16x16x32_bf16 v[10:13], v[142:145], v[230:233], v[10:13]
	s_add_i32 vcc_hi, vcc_hi, 2
	s_add_u32 s76, s76, 0x100
	s_addc_u32 s77, s77, 0
	s_add_u32 s87, s87, 0x100
	s_addc_u32 vcc_lo, vcc_lo, 0
	v_mfma_f32_16x16x32_bf16 v[54:57], v[146:149], v[184:187], v[54:57]
	v_mfma_f32_16x16x32_bf16 v[54:57], v[150:153], v[188:191], v[54:57]
	v_mfma_f32_16x16x32_bf16 v[50:53], v[154:157], v[184:187], v[50:53]
	v_mfma_f32_16x16x32_bf16 v[50:53], v[158:161], v[188:191], v[50:53]
	v_mfma_f32_16x16x32_bf16 v[38:41], v[146:149], v[198:201], v[38:41]
	v_mfma_f32_16x16x32_bf16 v[38:41], v[150:153], v[214:217], v[38:41]
	v_mfma_f32_16x16x32_bf16 v[34:37], v[154:157], v[198:201], v[34:37]
	v_mfma_f32_16x16x32_bf16 v[34:37], v[158:161], v[214:217], v[34:37]
	v_mfma_f32_16x16x32_bf16 v[22:25], v[146:149], v[218:221], v[22:25]
	v_mfma_f32_16x16x32_bf16 v[22:25], v[150:153], v[222:225], v[22:25]
	v_mfma_f32_16x16x32_bf16 v[18:21], v[154:157], v[218:221], v[18:21]
	v_mfma_f32_16x16x32_bf16 v[18:21], v[158:161], v[222:225], v[18:21]
	v_mfma_f32_16x16x32_bf16 v[6:9], v[146:149], v[226:229], v[6:9]
	v_mfma_f32_16x16x32_bf16 v[6:9], v[150:153], v[230:233], v[6:9]
	v_mfma_f32_16x16x32_bf16 v[2:5], v[154:157], v[226:229], v[2:5]
	v_mfma_f32_16x16x32_bf16 v[2:5], v[158:161], v[230:233], v[2:5]
	s_barrier
	s_cmp_gt_u32 vcc_hi, 13
	s_cbranch_scc0 .LBB0_778
	s_setprio 0
	s_cmp_eq_u64 s[50:51], 0
	s_cbranch_scc1 .Lpx_778
	s_setprio 1
.Lpx_778:
	s_and_b64 vcc, exec, s[50:51]
	s_cbranch_vccz .LBB0_781
	s_barrier

.LBB0_849:
	s_ashr_i32 s79, s78, 31
	s_lshl_b64 s[20:21], s[78:79], 19
	s_add_u32 s88, s4, s20
	s_addc_u32 s89, s5, s21
	s_and_b64 s[20:21], s[54:55], exec
	s_cselect_b32 s76, s89, s57
	s_cselect_b32 s77, s88, s56
	s_ashr_i32 s69, s68, 31
	s_lshl_b64 s[20:21], s[68:69], 19
	v_readlane_b32 s12, v247, 42
	s_add_u32 s94, s12, s20
	v_readlane_b32 s12, v245, 61
	s_addc_u32 s95, s12, s21
	s_and_b64 s[20:21], s[54:55], exec
	s_cselect_b32 s69, s95, s59
	s_cselect_b32 s79, s94, s58
	s_add_u32 s56, s56, 0x40080
	s_addc_u32 s57, s57, 0
	s_add_u32 s86, s58, 0x100
	v_mov_b32_e32 v2, 0
	s_addc_u32 s87, s59, 0
	s_mov_b32 s91, -2
	s_add_i32 vcc_lo, 0, 0x10000
	v_add_u32_e32 v158, vcc_lo, v145
	s_add_i32 vcc_hi, 0, 0x14000
	ds_read_b128 v[138:141], v158
	ds_read_b128 v[146:149], v158 offset:1024
	ds_read_b128 v[150:153], v158 offset:2048
	ds_read_b128 v[158:161], v158 offset:3072
	v_add_u32_e32 v194, vcc_hi, v145
	ds_read_b128 v[182:185], v194
	ds_read_b128 v[186:189], v194 offset:1024
	ds_read_b128 v[190:193], v194 offset:2048
	ds_read_b128 v[194:197], v194 offset:3072
	ds_read_b128 v[198:201], v157
	ds_read_b128 v[214:217], v157 offset:1024
	ds_read_b128 v[218:221], v157 offset:2048
	ds_read_b128 v[222:225], v157 offset:3072
	ds_read_b128 v[226:229], v157 offset:4096
	ds_read_b128 v[230:233], v157 offset:5120
	ds_read_b128 v[234:237], v157 offset:6144
	ds_read_b128 v[238:241], v157 offset:7168
	s_setprio 0
	s_cmp_eq_u64 s[62:63], 0
	s_cbranch_scc0 .Lpr_850
	s_setprio 1

.LBB0_850:
	s_add_i32 vcc_lo, 0, 0x10000
	v_add_u32_e32 v0, vcc_lo, v145
	s_add_i32 vcc_hi, 0, 0x14000
	ds_read_b128 v[138:141], v0
	ds_read_b128 v[146:149], v0 offset:1024
	ds_read_b128 v[150:153], v0 offset:2048
	ds_read_b128 v[158:161], v0 offset:3072
	v_add_u32_e32 v0, vcc_hi, v145
	ds_read_b128 v[182:185], v0
	ds_read_b128 v[186:189], v0 offset:1024
	ds_read_b128 v[190:193], v0 offset:2048
	ds_read_b128 v[194:197], v0 offset:3072
	ds_read_b128 v[198:201], v157
	ds_read_b128 v[214:217], v157 offset:1024
	ds_read_b128 v[218:221], v157 offset:2048
	ds_read_b128 v[222:225], v157 offset:3072
	ds_read_b128 v[226:229], v157 offset:4096
	ds_read_b128 v[230:233], v157 offset:5120
	ds_read_b128 v[234:237], v157 offset:6144
	ds_read_b128 v[238:241], v157 offset:7168
	s_add_u32 s20, s56, 0xfffc0080
	s_addc_u32 s21, s57, -1
	s_cmp_eq_u32 s91, 12
	s_cselect_b32 s59, s76, s21
	s_cselect_b32 s58, s77, s20
	s_cselect_b32 s21, s69, s87
	s_cselect_b32 s20, s79, s86
	s_add_i32 m0, s15, 0xc000
	v_lshl_add_u64 v[142:143], s[56:57], 0, v[136:137]
	global_load_lds_dwordx4 v[142:143], off
	v_lshl_add_u64 v[142:143], v[142:143], 0, s[72:73]
	s_add_i32 m0, s15, 0xe000
	s_nop 0
	global_load_lds_dwordx4 v[142:143], off
	s_waitcnt vmcnt(8)
	s_waitcnt lgkmcnt(0)
	s_barrier
	s_waitcnt lgkmcnt(0)
	v_mfma_f32_16x16x32_bf16 v[126:129], v[138:141], v[198:201], v[126:129]
	v_mfma_f32_16x16x32_bf16 v[126:129], v[146:149], v[214:217], v[126:129]
	v_mfma_f32_16x16x32_bf16 v[122:125], v[150:153], v[198:201], v[122:125]
	v_mfma_f32_16x16x32_bf16 v[122:125], v[158:161], v[214:217], v[122:125]
	v_mfma_f32_16x16x32_bf16 v[110:113], v[138:141], v[218:221], v[110:113]
	v_mfma_f32_16x16x32_bf16 v[110:113], v[146:149], v[222:225], v[110:113]
	v_mfma_f32_16x16x32_bf16 v[106:109], v[150:153], v[218:221], v[106:109]
	v_mfma_f32_16x16x32_bf16 v[106:109], v[158:161], v[222:225], v[106:109]
	v_mfma_f32_16x16x32_bf16 v[94:97], v[138:141], v[226:229], v[94:97]
	v_mfma_f32_16x16x32_bf16 v[94:97], v[146:149], v[230:233], v[94:97]
	v_mfma_f32_16x16x32_bf16 v[90:93], v[150:153], v[226:229], v[90:93]
	v_mfma_f32_16x16x32_bf16 v[90:93], v[158:161], v[230:233], v[90:93]
	v_mfma_f32_16x16x32_bf16 v[78:81], v[138:141], v[234:237], v[78:81]
	v_mfma_f32_16x16x32_bf16 v[78:81], v[146:149], v[238:241], v[78:81]
	v_mfma_f32_16x16x32_bf16 v[74:77], v[150:153], v[234:237], v[74:77]
	v_mfma_f32_16x16x32_bf16 v[74:77], v[158:161], v[238:241], v[74:77]
	v_mfma_f32_16x16x32_bf16 v[118:121], v[182:185], v[198:201], v[118:121]
	v_mfma_f32_16x16x32_bf16 v[118:121], v[186:189], v[214:217], v[118:121]
	v_mfma_f32_16x16x32_bf16 v[114:117], v[190:193], v[198:201], v[114:117]
	v_mfma_f32_16x16x32_bf16 v[114:117], v[194:197], v[214:217], v[114:117]
	v_mfma_f32_16x16x32_bf16 v[102:105], v[182:185], v[218:221], v[102:105]
	v_mfma_f32_16x16x32_bf16 v[102:105], v[186:189], v[222:225], v[102:105]
	v_mfma_f32_16x16x32_bf16 v[98:101], v[190:193], v[218:221], v[98:101]
	v_mfma_f32_16x16x32_bf16 v[98:101], v[194:197], v[222:225], v[98:101]
	v_mfma_f32_16x16x32_bf16 v[86:89], v[182:185], v[226:229], v[86:89]
	v_mfma_f32_16x16x32_bf16 v[86:89], v[186:189], v[230:233], v[86:89]
	v_mfma_f32_16x16x32_bf16 v[82:85], v[190:193], v[226:229], v[82:85]
	v_mfma_f32_16x16x32_bf16 v[82:85], v[194:197], v[230:233], v[82:85]
	v_mfma_f32_16x16x32_bf16 v[70:73], v[182:185], v[234:237], v[70:73]
	v_mfma_f32_16x16x32_bf16 v[70:73], v[186:189], v[238:241], v[70:73]
	v_mfma_f32_16x16x32_bf16 v[66:69], v[190:193], v[234:237], v[66:69]
	v_mfma_f32_16x16x32_bf16 v[66:69], v[194:197], v[238:241], v[66:69]
	s_barrier
	ds_read_b128 v[198:201], v157 offset:16384
	ds_read_b128 v[214:217], v157 offset:17408
	ds_read_b128 v[218:221], v157 offset:18432
	ds_read_b128 v[222:225], v157 offset:19456
	ds_read_b128 v[226:229], v157 offset:20480
	ds_read_b128 v[230:233], v157 offset:21504
	ds_read_b128 v[234:237], v157 offset:22528
	ds_read_b128 v[238:241], v157 offset:23552
	v_lshl_add_u64 v[142:143], s[20:21], 0, v[130:131]
	s_add_i32 s20, vcc_lo, s14
	s_mov_b32 m0, s20
	s_nop 0
	s_nop 0
	global_load_lds_dwordx4 v[142:143], off
	v_lshl_add_u64 v[162:163], v[142:143], 0, s[72:73]
	s_add_i32 m0, s20, 0x2000
	s_add_i32 s20, vcc_hi, s14
	global_load_lds_dwordx4 v[162:163], off
	v_lshl_add_u64 v[162:163], v[142:143], 0, s[28:29]
	s_mov_b32 m0, s20
	s_nop 0
	global_load_lds_dwordx4 v[162:163], off
	v_lshl_add_u64 v[162:163], v[142:143], 0, s[82:83]
	s_add_i32 m0, s20, 0x2000
	s_nop 0
	global_load_lds_dwordx4 v[162:163], off
	v_lshl_add_u64 v[162:163], s[58:59], 0, v[132:133]
	s_mov_b32 m0, s15
	v_lshl_add_u64 v[202:203], v[162:163], 0, s[72:73]
	global_load_lds_dwordx4 v[162:163], off
	s_mov_b32 m0, s42
	s_nop 0
	global_load_lds_dwordx4 v[202:203], off
	s_waitcnt vmcnt(8)
	s_waitcnt lgkmcnt(0)
	s_barrier
	s_waitcnt lgkmcnt(0)
	v_mfma_f32_16x16x32_bf16 v[62:65], v[138:141], v[198:201], v[62:65]
	v_mfma_f32_16x16x32_bf16 v[62:65], v[146:149], v[214:217], v[62:65]
	v_mfma_f32_16x16x32_bf16 v[58:61], v[150:153], v[198:201], v[58:61]
	v_mfma_f32_16x16x32_bf16 v[58:61], v[158:161], v[214:217], v[58:61]
	v_mfma_f32_16x16x32_bf16 v[46:49], v[138:141], v[218:221], v[46:49]
	v_mfma_f32_16x16x32_bf16 v[46:49], v[146:149], v[222:225], v[46:49]
	v_mfma_f32_16x16x32_bf16 v[42:45], v[150:153], v[218:221], v[42:45]
	v_mfma_f32_16x16x32_bf16 v[42:45], v[158:161], v[222:225], v[42:45]
	v_mfma_f32_16x16x32_bf16 v[30:33], v[138:141], v[226:229], v[30:33]
	v_mfma_f32_16x16x32_bf16 v[30:33], v[146:149], v[230:233], v[30:33]
	v_mfma_f32_16x16x32_bf16 v[26:29], v[150:153], v[226:229], v[26:29]
	v_mfma_f32_16x16x32_bf16 v[26:29], v[158:161], v[230:233], v[26:29]
	v_mfma_f32_16x16x32_bf16 v[14:17], v[138:141], v[234:237], v[14:17]
	v_mfma_f32_16x16x32_bf16 v[14:17], v[146:149], v[238:241], v[14:17]
	v_mfma_f32_16x16x32_bf16 v[10:13], v[150:153], v[234:237], v[10:13]
	v_mfma_f32_16x16x32_bf16 v[10:13], v[158:161], v[238:241], v[10:13]
	v_mfma_f32_16x16x32_bf16 v[54:57], v[182:185], v[198:201], v[54:57]
	v_mfma_f32_16x16x32_bf16 v[54:57], v[186:189], v[214:217], v[54:57]
	v_mfma_f32_16x16x32_bf16 v[50:53], v[190:193], v[198:201], v[50:53]
	v_mfma_f32_16x16x32_bf16 v[50:53], v[194:197], v[214:217], v[50:53]
	v_mfma_f32_16x16x32_bf16 v[38:41], v[182:185], v[218:221], v[38:41]
	v_mfma_f32_16x16x32_bf16 v[38:41], v[186:189], v[222:225], v[38:41]
	v_mfma_f32_16x16x32_bf16 v[34:37], v[190:193], v[218:221], v[34:37]
	v_mfma_f32_16x16x32_bf16 v[34:37], v[194:197], v[222:225], v[34:37]
	v_mfma_f32_16x16x32_bf16 v[22:25], v[182:185], v[226:229], v[22:25]
	v_mfma_f32_16x16x32_bf16 v[22:25], v[186:189], v[230:233], v[22:25]
	v_mfma_f32_16x16x32_bf16 v[18:21], v[190:193], v[226:229], v[18:21]
	v_mfma_f32_16x16x32_bf16 v[18:21], v[194:197], v[230:233], v[18:21]
	v_mfma_f32_16x16x32_bf16 v[6:9], v[182:185], v[234:237], v[6:9]
	v_mfma_f32_16x16x32_bf16 v[6:9], v[186:189], v[238:241], v[6:9]
	v_mfma_f32_16x16x32_bf16 v[2:5], v[190:193], v[234:237], v[2:5]
	v_mfma_f32_16x16x32_bf16 v[2:5], v[194:197], v[238:241], v[2:5]
	s_barrier
	s_add_i32 s20, 0, 0x18000
	v_add_u32_e32 v0, s20, v145
	s_add_i32 s21, 0, 0x1c000
	ds_read_b128 v[138:141], v0
	ds_read_b128 v[146:149], v0 offset:1024
	ds_read_b128 v[150:153], v0 offset:2048
	ds_read_b128 v[158:161], v0 offset:3072
	v_add_u32_e32 v0, s21, v145
	ds_read_b128 v[182:185], v0
	ds_read_b128 v[186:189], v0 offset:1024
	ds_read_b128 v[190:193], v0 offset:2048
	ds_read_b128 v[194:197], v0 offset:3072
	ds_read_b128 v[198:201], v157 offset:32768
	ds_read_b128 v[214:217], v157 offset:33792
	ds_read_b128 v[218:221], v157 offset:34816
	ds_read_b128 v[222:225], v157 offset:35840
	ds_read_b128 v[226:229], v157 offset:36864
	ds_read_b128 v[230:233], v157 offset:37888
	ds_read_b128 v[234:237], v157 offset:38912
	ds_read_b128 v[238:241], v157 offset:39936
	s_mov_b32 m0, s43
	v_lshl_add_u64 v[202:203], v[162:163], 0, s[28:29]
	global_load_lds_dwordx4 v[202:203], off
	v_lshl_add_u64 v[202:203], v[162:163], 0, s[82:83]
	s_mov_b32 m0, s46
	s_nop 0
	global_load_lds_dwordx4 v[202:203], off
	s_waitcnt vmcnt(8)
	s_waitcnt lgkmcnt(0)
	s_barrier
	s_waitcnt lgkmcnt(0)
	v_mfma_f32_16x16x32_bf16 v[126:129], v[138:141], v[198:201], v[126:129]
	v_mfma_f32_16x16x32_bf16 v[126:129], v[146:149], v[214:217], v[126:129]
	v_mfma_f32_16x16x32_bf16 v[122:125], v[150:153], v[198:201], v[122:125]
	v_mfma_f32_16x16x32_bf16 v[122:125], v[158:161], v[214:217], v[122:125]
	v_mfma_f32_16x16x32_bf16 v[110:113], v[138:141], v[218:221], v[110:113]
	v_mfma_f32_16x16x32_bf16 v[110:113], v[146:149], v[222:225], v[110:113]
	v_mfma_f32_16x16x32_bf16 v[106:109], v[150:153], v[218:221], v[106:109]
	v_mfma_f32_16x16x32_bf16 v[106:109], v[158:161], v[222:225], v[106:109]
	v_mfma_f32_16x16x32_bf16 v[94:97], v[138:141], v[226:229], v[94:97]
	v_mfma_f32_16x16x32_bf16 v[94:97], v[146:149], v[230:233], v[94:97]
	v_mfma_f32_16x16x32_bf16 v[90:93], v[150:153], v[226:229], v[90:93]
	v_mfma_f32_16x16x32_bf16 v[90:93], v[158:161], v[230:233], v[90:93]
	v_mfma_f32_16x16x32_bf16 v[78:81], v[138:141], v[234:237], v[78:81]
	v_mfma_f32_16x16x32_bf16 v[78:81], v[146:149], v[238:241], v[78:81]
	v_mfma_f32_16x16x32_bf16 v[74:77], v[150:153], v[234:237], v[74:77]
	v_mfma_f32_16x16x32_bf16 v[74:77], v[158:161], v[238:241], v[74:77]
	v_mfma_f32_16x16x32_bf16 v[118:121], v[182:185], v[198:201], v[118:121]
	v_mfma_f32_16x16x32_bf16 v[118:121], v[186:189], v[214:217], v[118:121]
	v_mfma_f32_16x16x32_bf16 v[114:117], v[190:193], v[198:201], v[114:117]
	v_mfma_f32_16x16x32_bf16 v[114:117], v[194:197], v[214:217], v[114:117]
	v_mfma_f32_16x16x32_bf16 v[102:105], v[182:185], v[218:221], v[102:105]
	v_mfma_f32_16x16x32_bf16 v[102:105], v[186:189], v[222:225], v[102:105]
	v_mfma_f32_16x16x32_bf16 v[98:101], v[190:193], v[218:221], v[98:101]
	v_mfma_f32_16x16x32_bf16 v[98:101], v[194:197], v[222:225], v[98:101]
	v_mfma_f32_16x16x32_bf16 v[86:89], v[182:185], v[226:229], v[86:89]
	v_mfma_f32_16x16x32_bf16 v[86:89], v[186:189], v[230:233], v[86:89]
	v_mfma_f32_16x16x32_bf16 v[82:85], v[190:193], v[226:229], v[82:85]
	v_mfma_f32_16x16x32_bf16 v[82:85], v[194:197], v[230:233], v[82:85]
	v_mfma_f32_16x16x32_bf16 v[70:73], v[182:185], v[234:237], v[70:73]
	v_mfma_f32_16x16x32_bf16 v[70:73], v[186:189], v[238:241], v[70:73]
	v_mfma_f32_16x16x32_bf16 v[66:69], v[190:193], v[234:237], v[66:69]
	v_mfma_f32_16x16x32_bf16 v[66:69], v[194:197], v[238:241], v[66:69]
	s_barrier
	ds_read_b128 v[198:201], v157 offset:49152
	ds_read_b128 v[214:217], v157 offset:50176
	ds_read_b128 v[218:221], v157 offset:51200
	ds_read_b128 v[222:225], v157 offset:52224
	ds_read_b128 v[226:229], v157 offset:53248
	ds_read_b128 v[230:233], v157 offset:54272
	ds_read_b128 v[234:237], v157 offset:55296
	ds_read_b128 v[238:241], v157 offset:56320
	s_add_i32 s20, s20, s14
	s_mov_b32 m0, s20
	v_lshl_add_u64 v[202:203], v[142:143], 0, s[34:35]
	global_load_lds_dwordx4 v[202:203], off
	v_lshl_add_u64 v[202:203], v[142:143], 0, s[38:39]
	s_add_i32 m0, s20, 0x2000
	s_add_i32 s20, s21, s14
	global_load_lds_dwordx4 v[202:203], off
	v_lshl_add_u64 v[202:203], v[142:143], 0, s[44:45]
	s_mov_b32 m0, s20
	v_lshl_add_u64 v[142:143], v[142:143], 0, s[10:11]
	global_load_lds_dwordx4 v[202:203], off
	s_add_i32 m0, s20, 0x2000
	s_nop 0
	global_load_lds_dwordx4 v[142:143], off
	v_lshl_add_u64 v[142:143], v[162:163], 0, s[34:35]
	s_mov_b32 m0, s47
	s_nop 0
	global_load_lds_dwordx4 v[142:143], off
	v_lshl_add_u64 v[142:143], v[162:163], 0, s[38:39]
	s_mov_b32 m0, s96
	s_nop 0
	global_load_lds_dwordx4 v[142:143], off
	s_waitcnt vmcnt(8)
	s_waitcnt lgkmcnt(0)
	s_barrier
	s_waitcnt lgkmcnt(0)
	v_mfma_f32_16x16x32_bf16 v[62:65], v[138:141], v[198:201], v[62:65]
	v_mfma_f32_16x16x32_bf16 v[62:65], v[146:149], v[214:217], v[62:65]
	v_mfma_f32_16x16x32_bf16 v[58:61], v[150:153], v[198:201], v[58:61]
	v_mfma_f32_16x16x32_bf16 v[58:61], v[158:161], v[214:217], v[58:61]
	v_mfma_f32_16x16x32_bf16 v[46:49], v[138:141], v[218:221], v[46:49]
	v_mfma_f32_16x16x32_bf16 v[46:49], v[146:149], v[222:225], v[46:49]
	v_mfma_f32_16x16x32_bf16 v[42:45], v[150:153], v[218:221], v[42:45]
	v_mfma_f32_16x16x32_bf16 v[42:45], v[158:161], v[222:225], v[42:45]
	v_mfma_f32_16x16x32_bf16 v[30:33], v[138:141], v[226:229], v[30:33]
	v_mfma_f32_16x16x32_bf16 v[30:33], v[146:149], v[230:233], v[30:33]
	v_mfma_f32_16x16x32_bf16 v[26:29], v[150:153], v[226:229], v[26:29]
	v_mfma_f32_16x16x32_bf16 v[26:29], v[158:161], v[230:233], v[26:29]
	v_mfma_f32_16x16x32_bf16 v[14:17], v[138:141], v[234:237], v[14:17]
	v_mfma_f32_16x16x32_bf16 v[14:17], v[146:149], v[238:241], v[14:17]
	v_mfma_f32_16x16x32_bf16 v[10:13], v[150:153], v[234:237], v[10:13]
	v_mfma_f32_16x16x32_bf16 v[10:13], v[158:161], v[238:241], v[10:13]
	s_add_i32 s91, s91, 2
	s_add_u32 s56, s56, 0x100
	s_addc_u32 s57, s57, 0
	s_add_u32 s86, s86, 0x100
	s_addc_u32 s87, s87, 0
	v_mfma_f32_16x16x32_bf16 v[54:57], v[182:185], v[198:201], v[54:57]
	v_mfma_f32_16x16x32_bf16 v[54:57], v[186:189], v[214:217], v[54:57]
	v_mfma_f32_16x16x32_bf16 v[50:53], v[190:193], v[198:201], v[50:53]
	v_mfma_f32_16x16x32_bf16 v[50:53], v[194:197], v[214:217], v[50:53]
	v_mfma_f32_16x16x32_bf16 v[38:41], v[182:185], v[218:221], v[38:41]
	v_mfma_f32_16x16x32_bf16 v[38:41], v[186:189], v[222:225], v[38:41]
	v_mfma_f32_16x16x32_bf16 v[34:37], v[190:193], v[218:221], v[34:37]
	v_mfma_f32_16x16x32_bf16 v[34:37], v[194:197], v[222:225], v[34:37]
	v_mfma_f32_16x16x32_bf16 v[22:25], v[182:185], v[226:229], v[22:25]
	v_mfma_f32_16x16x32_bf16 v[22:25], v[186:189], v[230:233], v[22:25]
	v_mfma_f32_16x16x32_bf16 v[18:21], v[190:193], v[226:229], v[18:21]
	v_mfma_f32_16x16x32_bf16 v[18:21], v[194:197], v[230:233], v[18:21]
	v_mfma_f32_16x16x32_bf16 v[6:9], v[182:185], v[234:237], v[6:9]
	v_mfma_f32_16x16x32_bf16 v[6:9], v[186:189], v[238:241], v[6:9]
	v_mfma_f32_16x16x32_bf16 v[2:5], v[190:193], v[234:237], v[2:5]
	v_mfma_f32_16x16x32_bf16 v[2:5], v[194:197], v[238:241], v[2:5]
	s_barrier
	s_cmp_gt_u32 s91, 13
	s_cbranch_scc0 .LBB0_850
	s_setprio 0
	s_cmp_eq_u64 s[62:63], 0
	s_cbranch_scc1 .Lpx_850
	s_setprio 1
.Lpx_850:
	s_and_b64 vcc, exec, s[62:63]
	s_cbranch_vccz .LBB0_853
	s_barrier

.LBB0_1060:
	s_setprio 0
	v_readlane_b32 s58, v245, 59
	v_readlane_b32 s59, v245, 60
	s_add_i32 s14, s58, 1
	s_cmp_lt_i32 s14, s59
	s_cselect_b64 s[0:1], -1, 0
	s_cmp_ge_i32 s14, s59
	s_cbranch_scc1 .LBB0_1114
	s_waitcnt vmcnt(0)
	s_waitcnt vmcnt(0) lgkmcnt(0)
	s_barrier
	s_mov_b64 s[4:5], exec
	v_readlane_b32 s6, v247, 4
	v_readlane_b32 s7, v247, 5
	s_and_b64 s[6:7], s[4:5], s[6:7]
	s_mov_b64 exec, s[6:7]
	s_cbranch_execz .LBB0_1113
	v_readlane_b32 s6, v245, 53
	s_waitcnt vmcnt(0) expcnt(0) lgkmcnt(0)
	s_nop 0
	v_mov_b32_e32 v0, s6
	ds_read_b32 v3, v0
	v_readlane_b32 s6, v245, 54
	s_waitcnt lgkmcnt(0)
	v_cmp_ne_u32_e32 vcc, 0, v3
	v_mov_b32_e32 v0, s6
	ds_read_b32 v2, v0
	s_cbranch_vccnz .LBB0_1077
	v_readlane_b32 s20, v247, 2
	v_readlane_b32 s21, v247, 3
	s_load_dwordx2 s[6:7], s[20:21], 0x4
	s_mov_b32 s20, 1
	s_waitcnt lgkmcnt(0)
	s_mul_i32 s15, s6, s66
	s_mul_i32 s15, s15, s7
	s_branch .LBB0_1065
